# sb static item remap for L1 sharing; XCD-contiguous expert tiles; sp3 load hoisting/batching; pool window loads batched
# speedup vs baseline: 1.0197x; 1.0197x over previous
;     __device__ bool next(int i, Unit& u) const {
;         int mt, pn;
;         if ((G & 7) == 0 && (G >> 3) % nN == 0) { const int xcd = c & 7, j = c >> 3, per = (G >> 3) / nN; pn = j % nN; mt = (i * per + j / nN) * 8 + xcd; }
;         else { const int L = i * G + c; mt = L / nN; pn = L % nN; }
;         if (mt >= MT) return false;
;         u.pm = mt; u.pn = pn; int e = 0;
;         for (int j = 1; j < NEXP; ++j) e += (mpre[j] <= mt) ? 1 : 0;
;         u.e = __builtin_amdgcn_readfirstlane(e); return true;
;     }
.LBB0_26:
	s_or_b64 exec, exec, s[0:1]
	v_readlane_b32 s0, v253, 63
	s_waitcnt lgkmcnt(0)
	s_barrier
	v_mov_b32_e32 v0, s0
	v_readlane_b32 s0, v249, 49
	s_and_b32 s0, s0, 31
	ds_read_b32 v0, v0
	s_cmp_lg_u32 s0, 0
	s_cselect_b64 s[16:17], -1, 0
	v_writelane_b32 v249, s16, 50
	s_cmp_eq_u32 s0, 0
	v_readlane_b32 s0, v251, 29
	v_writelane_b32 v249, s17, 51
	s_cselect_b64 s[16:17], -1, 0
	s_and_b64 s[20:21], s[16:17], exec
	v_readlane_b32 s1, v251, 31
	s_waitcnt lgkmcnt(0)
	v_readfirstlane_b32 s15, v0
	s_cselect_b32 s40, s1, s0
	s_lshr_b32 s98, s40, 3
	s_and_b32 s99, s40, 7
	s_add_i32 s100, s15, 7
	s_lshr_b32 s100, s100, 3
	s_mul_i32 s99, s99, s100
	s_add_i32 s40, s99, s98
	s_cmp_ge_u32 s98, s100
	s_cselect_b32 s40, 0x7fffffff, s40
	s_cmp_lt_i32 s40, s15
	s_cselect_b64 s[20:21], -1, 0
	s_cmp_ge_i32 s40, s15
	v_readfirstlane_b32 s12, v168
	s_cbranch_scc1 .LBB0_28
	v_readlane_b32 s0, v254, 0
	s_nop 1
	v_mov_b32_e32 v0, s0
	ds_read2_b32 v[0:1], v0 offset1:1
	v_readlane_b32 s0, v254, 1
	s_waitcnt lgkmcnt(0)
	v_cmp_ge_i32_e32 vcc, s40, v0
	v_mov_b32_e32 v0, s0
	s_nop 0
	v_cndmask_b32_e64 v2, 0, 1, vcc
	v_cmp_ge_i32_e32 vcc, s40, v1
	ds_read2_b32 v[0:1], v0 offset1:1
	v_readlane_b32 s0, v254, 2
	v_cndmask_b32_e64 v3, 0, 1, vcc
	s_waitcnt lgkmcnt(0)
	v_cmp_ge_i32_e32 vcc, s40, v0
	s_nop 1
	v_addc_co_u32_e32 v2, vcc, v3, v2, vcc
	v_mov_b32_e32 v0, s0
	v_cmp_ge_i32_e32 vcc, s40, v1
	ds_read2_b32 v[0:1], v0 offset1:1
	v_readlane_b32 s0, v254, 3
	v_cndmask_b32_e64 v3, 0, 1, vcc
	s_waitcnt lgkmcnt(0)
	v_cmp_ge_i32_e32 vcc, s40, v0
	s_nop 1
	v_addc_co_u32_e32 v2, vcc, v2, v3, vcc
	v_mov_b32_e32 v0, s0
	v_cmp_ge_i32_e32 vcc, s40, v1
	ds_read2_b32 v[0:1], v0 offset1:1
	v_readlane_b32 s0, v254, 4
	v_cndmask_b32_e64 v3, 0, 1, vcc
	s_waitcnt lgkmcnt(0)
	v_cmp_ge_i32_e32 vcc, s40, v0
	s_nop 1
	v_addc_co_u32_e32 v2, vcc, v2, v3, vcc
	v_mov_b32_e32 v0, s0
	v_cmp_ge_i32_e32 vcc, s40, v1
	ds_read2_b32 v[0:1], v0 offset1:1
	v_readlane_b32 s0, v254, 5
	v_cndmask_b32_e64 v3, 0, 1, vcc
	s_waitcnt lgkmcnt(0)
	v_cmp_ge_i32_e32 vcc, s40, v0
	s_nop 1
	v_addc_co_u32_e32 v2, vcc, v2, v3, vcc
	v_mov_b32_e32 v0, s0
	v_cmp_ge_i32_e32 vcc, s40, v1
	ds_read2_b32 v[0:1], v0 offset1:1
	v_readlane_b32 s0, v254, 6
	v_cndmask_b32_e64 v3, 0, 1, vcc
	s_waitcnt lgkmcnt(0)
	v_cmp_ge_i32_e32 vcc, s40, v0
	s_nop 1
	v_addc_co_u32_e32 v2, vcc, v2, v3, vcc
	v_mov_b32_e32 v0, s0
	v_cmp_ge_i32_e32 vcc, s40, v1
	ds_read2_b32 v[0:1], v0 offset1:1
	v_readlane_b32 s0, v254, 7
	v_cndmask_b32_e64 v3, 0, 1, vcc
	s_waitcnt lgkmcnt(0)
	v_cmp_ge_i32_e32 vcc, s40, v0
	s_nop 1
	v_addc_co_u32_e32 v2, vcc, v2, v3, vcc
	v_mov_b32_e32 v0, s0
	v_cmp_ge_i32_e32 vcc, s40, v1
	ds_read2_b32 v[0:1], v0 offset1:1
	v_readlane_b32 s0, v254, 8
	v_cndmask_b32_e64 v3, 0, 1, vcc
	s_waitcnt lgkmcnt(0)
	v_cmp_ge_i32_e32 vcc, s40, v0
	s_nop 1
	v_addc_co_u32_e32 v2, vcc, v2, v3, vcc
	v_mov_b32_e32 v0, s0
	v_cmp_ge_i32_e32 vcc, s40, v1
	ds_read2_b32 v[0:1], v0 offset1:1
	v_readlane_b32 s0, v254, 9
	v_cndmask_b32_e64 v3, 0, 1, vcc
	s_waitcnt lgkmcnt(0)
	v_cmp_ge_i32_e32 vcc, s40, v0
	s_nop 1
	v_addc_co_u32_e32 v2, vcc, v2, v3, vcc
	v_mov_b32_e32 v0, s0
	v_cmp_ge_i32_e32 vcc, s40, v1
	ds_read2_b32 v[0:1], v0 offset1:1
	v_readlane_b32 s0, v254, 10
	v_cndmask_b32_e64 v3, 0, 1, vcc
	s_waitcnt lgkmcnt(0)
	v_cmp_ge_i32_e32 vcc, s40, v0
	s_nop 1
	v_addc_co_u32_e32 v2, vcc, v2, v3, vcc
	v_mov_b32_e32 v0, s0
	v_cmp_ge_i32_e32 vcc, s40, v1
	ds_read2_b32 v[0:1], v0 offset1:1
	v_readlane_b32 s0, v254, 11
	v_cndmask_b32_e64 v3, 0, 1, vcc
	s_waitcnt lgkmcnt(0)
	v_cmp_ge_i32_e32 vcc, s40, v0
	s_nop 1
	v_addc_co_u32_e32 v2, vcc, v2, v3, vcc
	v_mov_b32_e32 v0, s0
	v_cmp_ge_i32_e32 vcc, s40, v1
	ds_read2_b32 v[0:1], v0 offset1:1
	v_readlane_b32 s0, v254, 12
	v_cndmask_b32_e64 v3, 0, 1, vcc
	s_waitcnt lgkmcnt(0)
	v_cmp_ge_i32_e32 vcc, s40, v0
	s_nop 1
	v_addc_co_u32_e32 v2, vcc, v2, v3, vcc
	v_mov_b32_e32 v0, s0
	v_cmp_ge_i32_e32 vcc, s40, v1
	ds_read2_b32 v[0:1], v0 offset1:1
	v_readlane_b32 s0, v254, 13
	v_cndmask_b32_e64 v3, 0, 1, vcc
	s_waitcnt lgkmcnt(0)
	v_cmp_ge_i32_e32 vcc, s40, v0
	s_nop 1
	v_addc_co_u32_e32 v2, vcc, v2, v3, vcc
	v_mov_b32_e32 v0, s0
	v_cmp_ge_i32_e32 vcc, s40, v1
	ds_read2_b32 v[0:1], v0 offset1:1
	v_readlane_b32 s0, v254, 14
	v_cndmask_b32_e64 v3, 0, 1, vcc
	s_waitcnt lgkmcnt(0)
	v_cmp_ge_i32_e32 vcc, s40, v0
	s_nop 1
	v_addc_co_u32_e32 v2, vcc, v2, v3, vcc
	v_mov_b32_e32 v0, s0
	v_cmp_ge_i32_e32 vcc, s40, v1
	ds_read2_b32 v[0:1], v0 offset1:1
	v_readlane_b32 s0, v254, 15
	v_cndmask_b32_e64 v3, 0, 1, vcc
	s_waitcnt lgkmcnt(0)
	v_cmp_ge_i32_e32 vcc, s40, v0
	s_nop 1
	v_addc_co_u32_e32 v0, vcc, v2, v3, vcc
	v_mov_b32_e32 v2, s0
	ds_read_b32 v2, v2
	v_cmp_ge_i32_e32 vcc, s40, v1
	s_nop 1
	v_cndmask_b32_e64 v1, 0, 1, vcc
	s_waitcnt lgkmcnt(0)
	v_cmp_ge_i32_e32 vcc, s40, v2
	s_nop 1
	v_addc_co_u32_e32 v0, vcc, v0, v1, vcc
	s_nop 0
	v_readfirstlane_b32 s56, v0

;     __device__ bool next(int i, Unit& u) const {
;         int mt, pn;
;         if ((G & 7) == 0 && (G >> 3) % nN == 0) { const int xcd = c & 7, j = c >> 3, per = (G >> 3) / nN; pn = j % nN; mt = (i * per + j / nN) * 8 + xcd; }
;         else { const int L = i * G + c; mt = L / nN; pn = L % nN; }
;         if (mt >= MT) return false;
;         u.pm = mt; u.pn = pn; int e = 0;
;         for (int j = 1; j < NEXP; ++j) e += (mpre[j] <= mt) ? 1 : 0;
;         u.e = __builtin_amdgcn_readfirstlane(e); return true;
;     }
; template <bool GATHER, bool FP8, class Epi, class Sched>
; __device__ __forceinline__ void gemm_phase(LAS unsigned char* lds, const int tid, const int K, const Sched& S, const Epi& E) {
;     ...
;         const bool has_next = S.next(ui + 1, nxt);
.LBB0_37:
	s_andn2_b64 vcc, exec, s[26:27]
	s_cbranch_vccnz .LBB0_39
	s_mul_i32 s0, s16, s95
	v_readlane_b32 s1, v251, 30
	s_add_i32 s0, s0, s1
	s_lshl_b32 s0, s0, 3
	v_readlane_b32 s1, v251, 37
	s_or_b32 s12, s0, s1
	s_lshr_b32 s98, s12, 3
	s_and_b32 s99, s12, 7
	s_add_i32 s100, s15, 7
	s_lshr_b32 s100, s100, 3
	s_mul_i32 s99, s99, s100
	s_add_i32 s12, s99, s98
	s_cmp_ge_u32 s98, s100
	s_cselect_b32 s12, 0x7fffffff, s12
	v_readlane_b32 s17, v251, 34

; #define LAS __attribute__((address_space(3)))
;     __device__ bool next(int i, Unit& u) const {
;     ...
;         if ((G & 7) == 0 && (G >> 3) % nN == 0) { const int xcd = c & 7, j = c >> 3, per = (G >> 3) / nN; pn = j % nN; mt = (i * per + j / nN) * 8 + xcd; }
;         else { const int L = i * G + c; mt = L / nN; pn = L % nN; }
;         if (mt >= MT) return false;
; __device__ __forceinline__ void run_phase(const Args& a, const int ph, LAS unsigned char* lds, const int tid, const int rpt) {
;     ...
;                 { LAS unsigned short* RT = (LAS unsigned short*)(lds + TAB_OFF + 256); const int* rowslot = (const int*)(ws + WS_ROWSLOT);
;                   for (int idx = tid; idx < 31 * 256; idx += 512) { pg8::Unit u; if (S.next(idx >> 8, u)) RT[idx] = (unsigned short)(rowslot[u.pm * 256 + (idx & 255)] >> 2); }
.LBB0_77:
	v_mul_lo_u32 v3, v3, s26
	v_readlane_b32 s22, v251, 35
	s_nop 1
	v_add_u32_e32 v3, s22, v3
	v_readlane_b32 s22, v251, 37
	s_nop 1
	s_add_i32 s36, s15, 7
	s_lshr_b32 s36, s36, 3
	s_mul_i32 s37, s22, s36
	v_add_u32_e32 v4, s37, v3
	v_cmp_le_u32_e32 vcc, s36, v3
	v_mov_b32_e32 v5, 0x7fffffff
	s_nop 1
	v_cndmask_b32_e32 v4, v4, v5, vcc

;     __device__ bool next(int i, Unit& u) const {
;     ...
;         if ((G & 7) == 0 && (G >> 3) % nN == 0) { const int xcd = c & 7, j = c >> 3, per = (G >> 3) / nN; pn = j % nN; mt = (i * per + j / nN) * 8 + xcd; }
;         else { const int L = i * G + c; mt = L / nN; pn = L % nN; }
;         if (mt >= MT) return false;
; __device__ __forceinline__ void run_phase(const Args& a, const int ph, LAS unsigned char* lds, const int tid, const int rpt) {
;     ...
;                   __syncthreads(); S.rt = RT; }
.LBB0_81:
	s_or_b64 exec, exec, s[0:1]
	s_cmp_lg_u32 s12, 0
	s_cselect_b64 s[0:1], -1, 0
	s_cmp_eq_u32 s12, 0
	s_cselect_b64 s[16:17], -1, 0
	s_and_b64 s[20:21], s[16:17], exec
	v_readlane_b32 s12, v253, 28
	v_readlane_b32 s20, v251, 38
	s_cselect_b32 s93, s20, s12
	s_lshr_b32 s98, s93, 3
	s_and_b32 s99, s93, 7
	s_add_i32 s100, s15, 7
	s_lshr_b32 s100, s100, 3
	s_mul_i32 s99, s99, s100
	s_add_i32 s93, s99, s98
	s_cmp_ge_u32 s98, s100
	s_cselect_b32 s93, 0x7fffffff, s93
	s_cmp_ge_i32 s93, s15
	v_readfirstlane_b32 s12, v168
	s_waitcnt lgkmcnt(0)
	s_barrier
	s_cbranch_scc1 .LBB0_105
; #define PG8_LOADOFF(dst, round) do { _Pragma("unroll") for (int _i = 0; _i < 2; ++_i) \
;         _Pragma("unroll") for (int _h = 0; _h < 2; ++_h) dst[_h][_i] = GATHER ? ((unsigned)S.rt[(round) * 256 + _h * 128 + _i * 64 + R0] * (unsigned)(K * 2) + (unsigned)(C0 * 2)) : voffA[_i]; } while (0)
; template <bool GATHER, bool FP8, class Epi, class Sched>
; __device__ __forceinline__ void gemm_phase(LAS unsigned char* lds, const int tid, const int K, const Sched& S, const Epi& E) {
;     const int wid = __builtin_amdgcn_readfirstlane(tid >> 6), lane = tid & 63, wr = wid >> 2, wc = wid & 3, fr = lane & 15, fq = lane >> 4;
;     const int nt = K / BK;
;     int R0, C0; stage_rc(tid * 16, R0, C0); const int Rb0 = Epi::PERM ? ((R0 & ~31) + perm32(R0 & 31)) : R0;
;     unsigned voffA[2], voffB[2];
;     voffA[0] = (unsigned)(R0 * K + C0) * 2u; voffA[1] = voffA[0] + (unsigned)(64 * K * 2);
;     voffB[0] = (unsigned)(Rb0 * 128 + C0 * 2); voffB[1] = voffB[0] + 64u * 128u;
;     const size_t kstepB = 32768, hstepB = 16384;
;     const size_t kstep = (size_t)(BK * 2);
;     const size_t hstep = (size_t)HALF * K * 2;
;     const size_t hsA = GATHER ? (size_t)0 : hstep;
;     unsigned oC[2][2], o2[2][2];
;     ...
;     const unsigned ldsw = (unsigned)wid * 1024u;
;     const int aoff = lds_byte(wr * 64 + fr, fq * 8), boff = lds_byte(wc * 32 + fr, fq * 8);
;     ...
;     Unit cur, nxt; int ui = 0;
;     if (!S.next(0, cur)) return;
;     int sc8 = 0x7f; asm volatile("" : "+v"(sc8));
;     float zf = 0.f; asm volatile("" : "+v"(zf));
;     f32x4 acc[2][2][4][2];
; #pragma unroll
;     for (int a = 0; a < 2; ++a)
; #pragma unroll
;         for (int b = 0; b < 2; ++b)
; #pragma unroll
;             for (int m = 0; m < 4; ++m)
; #pragma unroll
;                 for (int n = 0; n < 2; ++n) acc[a][b][m][n] = (f32x4){zf, zf, zf, zf};
;     bf16x8 At[4][2], B0[2][2], B1[2][2];
;     i32x8 At8[4], B08[2], B18[2];
;     const char* cA = S.aptr(cur); const char* cB = S.bptr(cur);
;     PG8_LOADOFF(oC, 0);
; #pragma unroll
;     for (int _h = 0; _h < 2; ++_h)
; #pragma unroll
;         for (int _i = 0; _i < 2; ++_i) o2[_h][_i] = oC[_h][_i];
;     PG8_STAGE(PG8_SB(0, 0), cB, voffB); PG8_STAGE(PG8_SB(0, 1), cB + hstepB, voffB); PG8_STAGE(PG8_SA(0, 0), cA, oC[0]); PG8_STAGE(PG8_SA(0, 1), cA + hsA, oC[1]);
	v_bfe_i32 v2, v168, 27, 1
	v_lshlrev_b32_e32 v0, 4, v168
	v_lshrrev_b32_e32 v2, 22, v2
	v_add_u32_e32 v2, v0, v2
	v_and_b32_e32 v2, 0xfffffc00, v2
	s_ashr_i32 s27, s12, 6
	v_sub_u32_e32 v0, v0, v2
	s_ashr_i32 s26, s12, 8
	v_lshrrev_b32_e32 v2, 4, v0
	s_lshl_b32 s36, s27, 10
	v_bitop3_b32 v0, v2, v0, 32 bitop3:0x6c
	s_and_b64 s[16:17], s[16:17], exec
	v_ashrrev_i32_e32 v3, 31, v0
	v_readlane_b32 s16, v251, 12
	v_readlane_b32 s17, v251, 34
	v_ashrrev_i32_e32 v1, 31, v168
	v_lshrrev_b32_e32 v3, 26, v3
	s_cselect_b32 s16, s17, s16
	v_lshrrev_b32_e32 v1, 26, v1
	v_add_u32_e32 v3, v0, v3
	s_ashr_i32 s17, s16, 31
	v_add_u32_e32 v1, v168, v1
	v_ashrrev_i32_e32 v4, 6, v3
	v_and_b32_e32 v3, 0xc0, v3
	s_lshr_b32 s17, s17, 29
	v_ashrrev_i32_e32 v1, 6, v1
	v_sub_u32_e32 v0, v0, v3
	v_mov_b32_e32 v3, 1
	s_add_i32 s17, s16, s17
	v_lshlrev_b32_e32 v2, 5, v1
	v_ashrrev_i16_sdwa v0, v3, sext(v0) dst_sel:DWORD dst_unused:UNUSED_PAD src0_sel:DWORD src1_sel:BYTE_0
	s_and_b32 s17, s17, -8
	v_and_b32_e32 v2, 32, v2
	v_bfe_i32 v0, v0, 0, 16
	s_sub_i32 s46, s16, s17
	v_readlane_b32 s16, v254, 0
	v_add_lshl_u32 v39, v2, v0, 1
	v_lshlrev_b32_e32 v0, 3, v1
	v_mov_b32_e32 v1, s16
	ds_read2_b32 v[2:3], v1 offset1:1
	v_readlane_b32 s16, v254, 1
	v_and_b32_e32 v0, -16, v0
	v_add_u32_e32 v0, v4, v0
	v_lshl_add_u32 v172, v0, 7, v39
	s_waitcnt lgkmcnt(0)
	v_cmp_ge_i32_e32 vcc, s93, v2
	v_mov_b32_e32 v2, s16
	v_readlane_b32 s16, v254, 2
	v_cndmask_b32_e64 v1, 0, 1, vcc
	v_cmp_ge_i32_e32 vcc, s93, v3
	ds_read2_b32 v[2:3], v2 offset1:1
	v_lshl_add_u32 v0, v0, 1, 0
	v_cndmask_b32_e64 v4, 0, 1, vcc
	v_mov_b32_e32 v169, 0x7f
	v_mov_b32_e32 v186, v33
	s_waitcnt lgkmcnt(0)
	v_cmp_ge_i32_e32 vcc, s93, v2
	v_mov_b32_e32 v2, s16
	v_readlane_b32 s16, v254, 3
	v_addc_co_u32_e32 v1, vcc, v4, v1, vcc
	v_cmp_ge_i32_e32 vcc, s93, v3
	ds_read2_b32 v[2:3], v2 offset1:1
	v_add_u32_e32 v187, 0x20100, v0
	v_cndmask_b32_e64 v4, 0, 1, vcc
	s_ashr_i32 s47, s46, 31
	s_lshl_b64 s[22:23], s[46:47], 18
	s_waitcnt lgkmcnt(0)
	v_cmp_ge_i32_e32 vcc, s93, v2
	v_mov_b32_e32 v2, s16
	v_readlane_b32 s16, v254, 4
	v_addc_co_u32_e32 v1, vcc, v1, v4, vcc
	v_cmp_ge_i32_e32 vcc, s93, v3
	ds_read2_b32 v[2:3], v2 offset1:1
	v_add_u32_e32 v174, 0x2000, v172
	v_cndmask_b32_e64 v4, 0, 1, vcc
	v_writelane_b32 v249, s71, 53
	s_waitcnt lgkmcnt(0)
	v_cmp_ge_i32_e32 vcc, s93, v2
	v_mov_b32_e32 v2, s16
	s_nop 0
	v_addc_co_u32_e32 v1, vcc, v1, v4, vcc
	v_cmp_ge_i32_e32 vcc, s93, v3
	ds_read2_b32 v[2:3], v2 offset1:1
	v_readlane_b32 s16, v254, 5
	v_cndmask_b32_e64 v4, 0, 1, vcc
	s_waitcnt lgkmcnt(0)
	v_cmp_ge_i32_e32 vcc, s93, v2
	s_nop 1
	v_addc_co_u32_e32 v1, vcc, v1, v4, vcc
	v_mov_b32_e32 v2, s16
	v_cmp_ge_i32_e32 vcc, s93, v3
	ds_read2_b32 v[2:3], v2 offset1:1
	v_readlane_b32 s16, v254, 6
	v_cndmask_b32_e64 v4, 0, 1, vcc
	s_waitcnt lgkmcnt(0)
	v_cmp_ge_i32_e32 vcc, s93, v2
	s_nop 1
	v_addc_co_u32_e32 v1, vcc, v1, v4, vcc
	v_mov_b32_e32 v2, s16
	v_cmp_ge_i32_e32 vcc, s93, v3
	ds_read2_b32 v[2:3], v2 offset1:1
	v_readlane_b32 s16, v254, 7
	v_cndmask_b32_e64 v4, 0, 1, vcc
	s_waitcnt lgkmcnt(0)
	v_cmp_ge_i32_e32 vcc, s93, v2
	s_nop 1
	v_addc_co_u32_e32 v1, vcc, v1, v4, vcc
	v_mov_b32_e32 v2, s16
	v_cmp_ge_i32_e32 vcc, s93, v3
	ds_read2_b32 v[2:3], v2 offset1:1
	v_readlane_b32 s16, v254, 8
	v_cndmask_b32_e64 v4, 0, 1, vcc
	s_waitcnt lgkmcnt(0)
	v_cmp_ge_i32_e32 vcc, s93, v2
	s_nop 1
	v_addc_co_u32_e32 v1, vcc, v1, v4, vcc
	v_mov_b32_e32 v2, s16
	v_cmp_ge_i32_e32 vcc, s93, v3
	ds_read2_b32 v[2:3], v2 offset1:1
	v_readlane_b32 s16, v254, 9
	v_cndmask_b32_e64 v4, 0, 1, vcc
	s_waitcnt lgkmcnt(0)
	v_cmp_ge_i32_e32 vcc, s93, v2
	s_nop 1
	v_addc_co_u32_e32 v1, vcc, v1, v4, vcc
	v_mov_b32_e32 v2, s16
	v_cmp_ge_i32_e32 vcc, s93, v3
	ds_read2_b32 v[2:3], v2 offset1:1
	v_readlane_b32 s16, v254, 10
	v_cndmask_b32_e64 v4, 0, 1, vcc
	s_waitcnt lgkmcnt(0)
	v_cmp_ge_i32_e32 vcc, s93, v2
	s_nop 1
	v_addc_co_u32_e32 v1, vcc, v1, v4, vcc
	v_mov_b32_e32 v2, s16
	v_cmp_ge_i32_e32 vcc, s93, v3
	ds_read2_b32 v[2:3], v2 offset1:1
	v_readlane_b32 s16, v254, 11
	v_cndmask_b32_e64 v4, 0, 1, vcc
	s_waitcnt lgkmcnt(0)
	v_cmp_ge_i32_e32 vcc, s93, v2
	s_nop 1
	v_addc_co_u32_e32 v1, vcc, v1, v4, vcc
	v_mov_b32_e32 v2, s16
	v_cmp_ge_i32_e32 vcc, s93, v3
	ds_read2_b32 v[2:3], v2 offset1:1
	v_readlane_b32 s16, v254, 12
	v_cndmask_b32_e64 v4, 0, 1, vcc
	s_waitcnt lgkmcnt(0)
	v_cmp_ge_i32_e32 vcc, s93, v2
	s_nop 1
	v_addc_co_u32_e32 v1, vcc, v1, v4, vcc
	v_mov_b32_e32 v2, s16
	v_cmp_ge_i32_e32 vcc, s93, v3
	ds_read2_b32 v[2:3], v2 offset1:1
	v_readlane_b32 s16, v254, 13
	v_cndmask_b32_e64 v4, 0, 1, vcc
	s_waitcnt lgkmcnt(0)
	v_cmp_ge_i32_e32 vcc, s93, v2
	s_nop 1
	v_addc_co_u32_e32 v1, vcc, v1, v4, vcc
	v_mov_b32_e32 v2, s16
	v_cmp_ge_i32_e32 vcc, s93, v3
	ds_read2_b32 v[2:3], v2 offset1:1
	v_readlane_b32 s16, v254, 14
	v_cndmask_b32_e64 v4, 0, 1, vcc
	s_waitcnt lgkmcnt(0)
	v_cmp_ge_i32_e32 vcc, s93, v2
	s_nop 1
	v_addc_co_u32_e32 v1, vcc, v1, v4, vcc
	v_mov_b32_e32 v2, s16
	v_cmp_ge_i32_e32 vcc, s93, v3
	ds_read2_b32 v[2:3], v2 offset1:1
	v_readlane_b32 s16, v254, 15
	v_cndmask_b32_e64 v4, 0, 1, vcc
	s_waitcnt lgkmcnt(0)
	v_cmp_ge_i32_e32 vcc, s93, v2
	s_nop 1
	v_addc_co_u32_e32 v1, vcc, v1, v4, vcc
	v_cmp_ge_i32_e32 vcc, s93, v3
	v_mov_b32_e32 v3, s16
	ds_read_b32 v3, v3
	ds_read_u16 v0, v187
	v_cndmask_b32_e64 v2, 0, 1, vcc
	s_waitcnt lgkmcnt(0)
	v_cmp_ge_i32_e32 vcc, s93, v3
	s_waitcnt lgkmcnt(0)
	v_lshl_add_u32 v32, v0, 10, v39
	v_addc_co_u32_e32 v1, vcc, v1, v2, vcc
	ds_read_u16 v0, v187 offset:256
	v_readfirstlane_b32 s20, v1
	s_ashr_i32 s21, s20, 31
	s_lshl_b64 s[16:17], s[20:21], 21
	v_readlane_b32 s21, v254, 55
	s_add_u32 s16, s21, s16
	v_readlane_b32 s21, v254, 56
	s_waitcnt lgkmcnt(0)
	v_lshl_add_u32 v188, v0, 10, v39
	ds_read_u16 v0, v187 offset:128
	s_addc_u32 s17, s21, s17
	s_add_u32 s22, s16, s22
	s_addc_u32 s23, s17, s23
	s_add_i32 s47, s36, 0
	s_add_i32 s54, s47, 0x10000
	s_add_i32 s55, s47, 0x12000
	s_mov_b32 m0, s54
	s_add_u32 s16, s22, 0x4000
	s_waitcnt lgkmcnt(0)
	v_lshl_add_u32 v176, v0, 10, v39
	ds_read_u16 v0, v187 offset:384
	global_load_lds_dwordx4 v172, s[22:23]
	s_mov_b32 m0, s55
	s_addc_u32 s17, s23, 0
	s_add_i32 s56, s47, 0x14000
	global_load_lds_dwordx4 v174, s[22:23]
	s_mov_b32 m0, s56
	s_add_i32 s57, s47, 0x16000
	global_load_lds_dwordx4 v172, s[16:17]
	s_mov_b32 m0, s57
	s_add_i32 s58, s47, 0x2000
	global_load_lds_dwordx4 v174, s[16:17]
	s_mov_b32 m0, s47
	s_add_i32 s59, s47, 0x4000
	global_load_lds_dwordx4 v32, s[6:7]
	s_mov_b32 m0, s58
	s_add_i32 s60, s47, 0x6000
	global_load_lds_dwordx4 v176, s[6:7]
	s_mov_b32 m0, s59
	s_waitcnt lgkmcnt(0)
	v_lshl_add_u32 v190, v0, 10, v39
	global_load_lds_dwordx4 v188, s[6:7]
	s_mov_b32 m0, s60
	s_cmp_eq_u32 s26, 1
	global_load_lds_dwordx4 v190, s[6:7]
	s_cselect_b64 s[16:17], -1, 0
	v_writelane_b32 v249, s16, 54
	s_cmp_lg_u32 s26, 1
	s_nop 0
	v_writelane_b32 v249, s17, 55
	s_cbranch_scc1 .LBB0_84
	s_barrier

;     __device__ bool next(int i, Unit& u) const {
;         int mt, pn;
;         if ((G & 7) == 0 && (G >> 3) % nN == 0) { const int xcd = c & 7, j = c >> 3, per = (G >> 3) / nN; pn = j % nN; mt = (i * per + j / nN) * 8 + xcd; }
;         else { const int L = i * G + c; mt = L / nN; pn = L % nN; }
;         if (mt >= MT) return false;
;         u.pm = mt; u.pn = pn; int e = 0;
;         for (int j = 1; j < NEXP; ++j) e += (mpre[j] <= mt) ? 1 : 0;
;         u.e = __builtin_amdgcn_readfirstlane(e); return true;
;     }
; template <bool GATHER, bool FP8, class Epi, class Sched>
; __device__ __forceinline__ void gemm_phase(LAS unsigned char* lds, const int tid, const int K, const Sched& S, const Epi& E) {
;     ...
;         const bool has_next = S.next(ui + 1, nxt);
.LBB0_98:
	v_readlane_b32 s12, v249, 52
	s_mul_i32 s12, s73, s12
	v_readlane_b32 s16, v251, 35
	s_add_i32 s12, s12, s16
	s_lshl_b32 s12, s12, 3
	v_readlane_b32 s16, v251, 37
	s_or_b32 s12, s12, s16
	s_lshr_b32 s98, s12, 3
	s_and_b32 s99, s12, 7
	s_add_i32 s100, s15, 7
	s_lshr_b32 s100, s100, 3
	s_mul_i32 s99, s99, s100
	s_add_i32 s12, s99, s98
	s_cmp_ge_u32 s98, s100
	s_cselect_b32 s12, 0x7fffffff, s12
	v_readlane_b32 s16, v251, 34
	s_cmp_lt_i32 s12, s15
	s_cselect_b64 s[44:45], -1, 0
	s_cmp_ge_i32 s12, s15
	s_cbranch_scc0 .LBB0_90
	s_branch .LBB0_91

; #define LAS __attribute__((address_space(3)))
; __device__ __forceinline__ unsigned pk2(float lo, float hi) { unsigned r; asm("v_cvt_pk_bf16_f32 %0, %1, %2" : "=v"(r) : "v"(lo), "v"(hi)); return r; }
; __device__ __forceinline__ float bflo(unsigned u) { return __uint_as_float(u << 16); }
; __device__ __forceinline__ float bfhi(unsigned u) { return __uint_as_float(u & 0xffff0000u); }
; __device__ __forceinline__ float log2_gamma(int h) { return log2f(1.0f - exp2f(-5.0f - (float)h)); }
; template <bool SCALE>
; __device__ __forceinline__ void load_tile_T(const bf16_t* src, LAS bf16_t* T, int lane, float sc0, float scmul) {
;     const int cr = lane >> 3, dc = lane & 7;
;     u32x4 v[8];
; #pragma unroll
;     for (int i = 0; i < 8; ++i) v[i] = *(const u32x4*)(src + (size_t)(cr + 8 * i) * INWP + 8 * dc);
; #pragma unroll
;     for (int i = 0; i < 8; ++i) { const int row = cr + 8 * i; u32x4 w = v[i];
;         if (SCALE) { const float s = sc0 * __builtin_amdgcn_exp2f(scmul * (float)row);
;             w.x = pk2(bflo(w.x) * s, bfhi(w.x) * s); w.y = pk2(bflo(w.y) * s, bfhi(w.y) * s); w.z = pk2(bflo(w.z) * s, bfhi(w.z) * s); w.w = pk2(bflo(w.w) * s, bfhi(w.w) * s); }
;         LAS bf16_t* t = T + (8 * dc) * TLD + row;
;         t[0 * TLD] = (bf16_t)(w.x & 0xffff); t[1 * TLD] = (bf16_t)(w.x >> 16); t[2 * TLD] = (bf16_t)(w.y & 0xffff); t[3 * TLD] = (bf16_t)(w.y >> 16);
;         t[4 * TLD] = (bf16_t)(w.z & 0xffff); t[5 * TLD] = (bf16_t)(w.z >> 16); t[6 * TLD] = (bf16_t)(w.w & 0xffff); t[7 * TLD] = (bf16_t)(w.w >> 16); }
; __device__ __forceinline__ void retout_item(const bf16_t* hbuf, const float* rot, const float* kvbuf, const float* normg, bf16_t* mixed, LAS bf16_t* vT, int item, int lane) {
;     const int bh = item / NCHUNK, n = item % NCHUNK, b = bh / 6, h = bh % 6; const size_t t0 = (size_t)b * SEQ + (size_t)n * 64;
;     const int r = lane & 15, q = lane >> 4; const float l2g = log2_gamma(h);
;     load_tile_T<false>(hbuf + t0 * INWP + C_RV + h * 64, vT, lane, 0.f, 0.f);
.LBB0_175:
	s_ashr_i32 s1, s0, 31
	s_lshr_b32 s12, s1, 24
	s_add_i32 s12, s0, s12
	s_ashr_i32 s17, s12, 8
	s_and_b32 s12, s12, 0xffffff00
	s_sub_i32 s20, s0, s12
	s_mul_hi_i32 s12, s0, 0x2aaaaaab
	s_lshr_b32 s15, s12, 31
	s_ashr_i32 s12, s12, 8
	s_add_i32 s22, s12, s15
	s_mul_hi_i32 s12, s17, 0x2aaaaaab
	s_lshr_b32 s15, s12, 31
	s_add_i32 s12, s12, s15
	s_mul_i32 s12, s12, 6
	s_sub_i32 s15, s17, s12
	v_cvt_f32_i32_e32 v0, s15
	s_mov_b32 s12, 0xc2fc0000
	s_ashr_i32 s23, s22, 31
	s_ashr_i32 s21, s20, 31
	v_sub_f32_e32 v0, 0xc0a00000, v0
	v_cmp_gt_f32_e32 vcc, s12, v0
	s_lshl_b64 s[22:23], s[22:23], 14
	s_lshl_b64 s[26:27], s[20:21], 6
	v_cndmask_b32_e32 v1, 0, v229, vcc
	v_add_f32_e32 v0, v0, v1
	s_add_u32 s22, s22, s26
	v_exp_f32_e32 v0, v0
	s_addc_u32 s21, s23, s27
	s_and_b64 s[26:27], vcc, exec
	s_cselect_b32 s23, 0xffffffc0, 0
	v_ldexp_f32 v0, v0, s23
	s_mul_i32 s23, s21, 0x1800
	s_mul_hi_u32 s26, s22, 0x1800
	s_add_i32 s26, s26, s23
	s_mul_i32 s23, s22, 0x1800
	s_add_u32 s23, s42, s23
	s_addc_u32 s27, s43, s26
	s_lshl_b32 s38, s15, 6
	s_ashr_i32 s39, s38, 31
	s_lshl_b64 s[36:37], s[38:39], 1
	s_add_u32 s26, s23, s36
	s_addc_u32 s27, s27, s37
	v_sub_f32_e32 v53, 1.0, v0
	v_lshl_add_u64 v[0:1], s[26:27], 0, v[32:33]
	v_mov_b32_e32 v85, v33
	v_lshl_add_u64 v[24:25], v[0:1], 0, v[84:85]
	s_movk_i32 s15, 0x1000
	v_add_co_u32_e32 v0, vcc, s15, v24
	s_mov_b32 s15, 0xd000
	s_nop 0
	v_addc_co_u32_e32 v1, vcc, 0, v25, vcc
	global_load_dwordx4 v[0:3], v[0:1], off offset:256
	v_or_b32_e32 v52, s22, v60
	v_mov_b64_e32 v[44:45], s[42:43]
	v_mov_b32_e32 v87, v33
	v_mov_b32_e32 v89, v33
	v_mov_b32_e32 v91, v33
	v_mov_b32_e32 v93, v33
	v_mov_b32_e32 v95, v33
	s_mov_b32 s12, 0
	v_lshl_add_u64 v[96:97], s[38:39], 2, v[76:77]
	s_waitcnt vmcnt(0)
	ds_write_b16 v39, v0
	ds_write_b16_d16_hi v39, v0 offset:144
	ds_write_b16 v39, v1 offset:288
	ds_write_b16_d16_hi v39, v1 offset:432
	ds_write_b16 v39, v2 offset:576
	ds_write_b16_d16_hi v39, v2 offset:720
	ds_write_b16 v39, v3 offset:864
	ds_write_b16_d16_hi v39, v3 offset:1008
	v_add_co_u32_e32 v0, vcc, s15, v24
	s_mov_b32 s15, 0x19000
	s_nop 0
	v_addc_co_u32_e32 v1, vcc, 0, v25, vcc
	global_load_dwordx4 v[0:3], v[0:1], off offset:256
	v_add_co_u32_e32 v4, vcc, s15, v24
	s_mov_b32 s15, 0x25000
	s_nop 0
	v_addc_co_u32_e32 v5, vcc, 0, v25, vcc
	global_load_dwordx4 v[4:7], v[4:5], off offset:256
	v_add_co_u32_e32 v8, vcc, s15, v24
	s_mov_b32 s15, 0x31000
	s_nop 0
	v_addc_co_u32_e32 v9, vcc, 0, v25, vcc
	global_load_dwordx4 v[8:11], v[8:9], off offset:256
	v_add_co_u32_e32 v12, vcc, s15, v24
	s_mov_b32 s15, 0x3d000
	s_nop 0
	v_addc_co_u32_e32 v13, vcc, 0, v25, vcc
	global_load_dwordx4 v[12:15], v[12:13], off offset:256
	v_add_co_u32_e32 v16, vcc, s15, v24
	s_mov_b32 s15, 0x49000
	s_nop 0
	v_addc_co_u32_e32 v17, vcc, 0, v25, vcc
	global_load_dwordx4 v[16:19], v[16:17], off offset:256
	v_add_co_u32_e32 v20, vcc, s15, v24
	s_mov_b32 s15, 0x55000
	s_nop 0
	v_addc_co_u32_e32 v21, vcc, 0, v25, vcc
	global_load_dwordx4 v[20:23], v[20:21], off offset:256
	v_add_co_u32_e32 v24, vcc, s15, v24
	s_lshl_b32 s15, s20, 6
	s_nop 0
	v_addc_co_u32_e32 v25, vcc, 0, v25, vcc
	global_load_dwordx4 v[24:27], v[24:25], off offset:256
	v_cmp_gt_f32_e32 vcc, s33, v53
	s_waitcnt vmcnt(6)
	ds_write_b16 v39, v0 offset:16
	ds_write_b16_d16_hi v39, v0 offset:160
	ds_write_b16 v39, v1 offset:304
	ds_write_b16_d16_hi v39, v1 offset:448
	ds_write_b16 v39, v2 offset:592
	ds_write_b16_d16_hi v39, v2 offset:736
	ds_write_b16 v39, v3 offset:880
	ds_write_b16_d16_hi v39, v3 offset:1024
	s_waitcnt vmcnt(5)
	ds_write_b16 v39, v4 offset:32
	ds_write_b16_d16_hi v39, v4 offset:176
	ds_write_b16 v39, v5 offset:320
	ds_write_b16_d16_hi v39, v5 offset:464
	ds_write_b16 v39, v6 offset:608
	ds_write_b16_d16_hi v39, v6 offset:752
	ds_write_b16 v39, v7 offset:896
	ds_write_b16_d16_hi v39, v7 offset:1040
	s_waitcnt vmcnt(4)
	ds_write_b16 v39, v8 offset:48
	ds_write_b16_d16_hi v39, v8 offset:192
	ds_write_b16 v39, v9 offset:336
	ds_write_b16_d16_hi v39, v9 offset:480
	ds_write_b16 v39, v10 offset:624
	ds_write_b16_d16_hi v39, v10 offset:768
	ds_write_b16 v39, v11 offset:912
	ds_write_b16_d16_hi v39, v11 offset:1056
	s_waitcnt vmcnt(3)
	ds_write_b16 v39, v12 offset:64
	ds_write_b16_d16_hi v39, v12 offset:208
	ds_write_b16 v39, v13 offset:352
	ds_write_b16_d16_hi v39, v13 offset:496
	ds_write_b16 v39, v14 offset:640
	ds_write_b16_d16_hi v39, v14 offset:784
	ds_write_b16 v39, v15 offset:928
	ds_write_b16_d16_hi v39, v15 offset:1072
	s_waitcnt vmcnt(2)
	ds_write_b16 v39, v16 offset:80
	ds_write_b16_d16_hi v39, v16 offset:224
	ds_write_b16 v39, v17 offset:368
	ds_write_b16_d16_hi v39, v17 offset:512
	ds_write_b16 v39, v18 offset:656
	ds_write_b16_d16_hi v39, v18 offset:800
	ds_write_b16 v39, v19 offset:944
	ds_write_b16_d16_hi v39, v19 offset:1088
	s_waitcnt vmcnt(1)
	ds_write_b16 v39, v20 offset:96
	ds_write_b16_d16_hi v39, v20 offset:240
	ds_write_b16 v39, v21 offset:384
	ds_write_b16_d16_hi v39, v21 offset:528
	ds_write_b16 v39, v22 offset:672
	ds_write_b16_d16_hi v39, v22 offset:816
	ds_write_b16 v39, v23 offset:960
	ds_write_b16_d16_hi v39, v23 offset:1104
	s_waitcnt vmcnt(0)
; #define LAS __attribute__((address_space(3)))
; __device__ __forceinline__ unsigned pk2(float lo, float hi) { unsigned r; asm("v_cvt_pk_bf16_f32 %0, %1, %2" : "=v"(r) : "v"(lo), "v"(hi)); return r; }
; __device__ __forceinline__ float bflo(unsigned u) { return __uint_as_float(u << 16); }
; __device__ __forceinline__ float bfhi(unsigned u) { return __uint_as_float(u & 0xffff0000u); }
; __device__ __forceinline__ void rot8(u32x4 x1, u32x4 x2, const float* cs, const float* sn, float sc, u32x4& o1, u32x4& o2) {
;     const f32x4 c0 = *(const f32x4*)cs, c1 = *(const f32x4*)(cs + 4), s0 = *(const f32x4*)sn, s1 = *(const f32x4*)(sn + 4);
;     float a[8], b[8], c[8], s[8];
;     a[0] = bflo(x1.x); a[1] = bfhi(x1.x); a[2] = bflo(x1.y); a[3] = bfhi(x1.y); a[4] = bflo(x1.z); a[5] = bfhi(x1.z); a[6] = bflo(x1.w); a[7] = bfhi(x1.w);
;     b[0] = bflo(x2.x); b[1] = bfhi(x2.x); b[2] = bflo(x2.y); b[3] = bfhi(x2.y); b[4] = bflo(x2.z); b[5] = bfhi(x2.z); b[6] = bflo(x2.w); b[7] = bfhi(x2.w);
; #pragma unroll
;     for (int i = 0; i < 4; ++i) { c[i] = c0[i]; c[4 + i] = c1[i]; s[i] = s0[i]; s[4 + i] = s1[i]; }
;     float p[8], q[8];
; #pragma unroll
;     for (int i = 0; i < 8; ++i) { p[i] = (a[i] * c[i] - b[i] * s[i]) * sc; q[i] = (a[i] * s[i] + b[i] * c[i]) * sc; }
;     o1.x = pk2(p[0], p[1]); o1.y = pk2(p[2], p[3]); o1.z = pk2(p[4], p[5]); o1.w = pk2(p[6], p[7]);
;     o2.x = pk2(q[0], q[1]); o2.y = pk2(q[2], q[3]); o2.z = pk2(q[4], q[5]); o2.w = pk2(q[6], q[7]);
; }
; __device__ __forceinline__ void retout_item(const bf16_t* hbuf, const float* rot, const float* kvbuf, const float* normg, bf16_t* mixed, LAS bf16_t* vT, int item, int lane) {
;     ...
;     bf16x8 kf[4][2]; LAS bf16_t* RT = vT + 64 * TLD;
; #pragma unroll
;     for (int mt = 0; mt < 4; ++mt) { const int row = 16 * mt + r; const bf16_t* kp = hbuf + (t0 + row) * INWP + C_RK + h * 64 + 8 * q; const int pos = n * 64 + row; u32x4 o1, o2;
;         rot8(*(const u32x4*)kp, *(const u32x4*)(kp + 32), cs + (size_t)pos * 32 + 8 * q, sn + (size_t)pos * 32 + 8 * q, 0.125f, o1, o2); kf[mt][0] = as_bf16x8(o1); kf[mt][1] = as_bf16x8(o2); }
	ds_write_b16 v39, v24 offset:112
	ds_write_b16_d16_hi v39, v24 offset:256
	ds_write_b16 v39, v25 offset:400
	ds_write_b16_d16_hi v39, v25 offset:544
	ds_write_b16 v39, v26 offset:688
	ds_write_b16_d16_hi v39, v26 offset:832
	ds_write_b16 v39, v27 offset:976
	ds_write_b16_d16_hi v39, v27 offset:1120
	v_mad_u64_u32 v[0:1], s[26:27], v52, s5, v[44:45]
	v_or_b32_e32 v8, s15, v60
	v_mad_i32_i24 v1, s21, v207, v1
	v_ashrrev_i32_e32 v9, 31, v8
	v_lshl_add_u64 v[0:1], v[0:1], 0, s[36:37]
	v_lshlrev_b64 v[8:9], 7, v[8:9]
	v_lshl_add_u64 v[4:5], v[0:1], 0, v[86:87]
	v_lshl_add_u64 v[12:13], v[64:65], 0, v[8:9]
	v_lshl_add_u64 v[20:21], v[66:67], 0, v[8:9]
	global_load_dwordx4 v[0:3], v[4:5], off offset:3584
	s_nop 0
	global_load_dwordx4 v[4:7], v[4:5], off offset:3648
	s_nop 0
	global_load_dwordx4 v[8:11], v[12:13], off offset:16
	global_load_dwordx4 v[16:19], v[12:13], off
	s_nop 0
	global_load_dwordx4 v[12:15], v[20:21], off offset:16
	s_nop 0
	global_load_dwordx4 v[20:23], v[20:21], off
	s_waitcnt vmcnt(2)
	v_mov_b32_e32 v27, v16
	v_lshlrev_b32_e32 v25, 16, v0
	v_lshlrev_b32_e32 v24, 16, v4
	s_waitcnt vmcnt(0)
	v_mov_b32_e32 v26, v20
	v_pk_mul_f32 v[26:27], v[26:27], v[24:25]
	s_nop 0
	v_sub_f32_e32 v26, v27, v26
	v_mul_f32_e32 v28, 0x3e000000, v26
	v_mov_b32_e32 v26, v16
	v_mov_b32_e32 v27, v20
	v_pk_mul_f32 v[24:25], v[26:27], v[24:25]
	v_mov_b32_e32 v20, v17
	v_add_f32_e32 v16, v24, v25
	v_mul_f32_e32 v29, 0x3e000000, v16
	v_and_b32_e32 v25, 0xffff0000, v0
	v_and_b32_e32 v24, 0xffff0000, v4
	v_mov_b32_e32 v16, v21
	v_pk_mul_f32 v[26:27], v[16:17], v[24:25]
	v_pk_mul_f32 v[16:17], v[20:21], v[24:25]
	v_sub_f32_e32 v0, v27, v26
	v_mul_f32_e32 v26, 0x3e000000, v0
	v_add_f32_e32 v0, v16, v17
	v_lshlrev_b32_e32 v17, 16, v1
	v_lshlrev_b32_e32 v16, 16, v5
	v_mov_b32_e32 v20, v22
	v_mov_b32_e32 v21, v18
	v_pk_mul_f32 v[20:21], v[20:21], v[16:17]
	v_mul_f32_e32 v24, 0x3e000000, v0
	v_sub_f32_e32 v0, v21, v20
	v_mov_b32_e32 v20, v18
	v_mov_b32_e32 v21, v22
	v_pk_mul_f32 v[16:17], v[20:21], v[16:17]
	v_mul_f32_e32 v25, 0x3e000000, v0
	v_add_f32_e32 v0, v16, v17
	v_mul_f32_e32 v16, 0x3e000000, v0
	v_and_b32_e32 v1, 0xffff0000, v1
	v_and_b32_e32 v0, 0xffff0000, v5
	v_mov_b32_e32 v18, v23
	v_mov_b32_e32 v22, v19
	v_pk_mul_f32 v[4:5], v[18:19], v[0:1]
	v_pk_mul_f32 v[0:1], v[22:23], v[0:1]
	v_sub_f32_e32 v4, v5, v4
	v_add_f32_e32 v0, v0, v1
	v_mul_f32_e32 v17, 0x3e000000, v4
	v_mul_f32_e32 v18, 0x3e000000, v0
	v_lshlrev_b32_e32 v1, 16, v2
	v_lshlrev_b32_e32 v0, 16, v6
	v_mov_b32_e32 v4, v12
	v_mov_b32_e32 v5, v8
	v_pk_mul_f32 v[4:5], v[4:5], v[0:1]
	s_nop 0
	v_sub_f32_e32 v4, v5, v4
	v_mul_f32_e32 v19, 0x3e000000, v4
	v_mov_b32_e32 v4, v8
	v_mov_b32_e32 v5, v12
	v_pk_mul_f32 v[0:1], v[4:5], v[0:1]
	v_mov_b32_e32 v8, v13
	v_add_f32_e32 v0, v0, v1
	v_mul_f32_e32 v20, 0x3e000000, v0
	v_and_b32_e32 v1, 0xffff0000, v2
	v_and_b32_e32 v0, 0xffff0000, v6
	v_mov_b32_e32 v12, v9
	v_pk_mul_f32 v[4:5], v[8:9], v[0:1]
	v_pk_mul_f32 v[0:1], v[12:13], v[0:1]
	v_sub_f32_e32 v2, v5, v4
	v_add_f32_e32 v0, v0, v1
	v_mul_f32_e32 v8, 0x3e000000, v0
	v_lshlrev_b32_e32 v1, 16, v3
	v_lshlrev_b32_e32 v0, 16, v7
	v_mov_b32_e32 v4, v14
	v_mov_b32_e32 v5, v10
	v_pk_mul_f32 v[4:5], v[4:5], v[0:1]
	v_mul_f32_e32 v6, 0x3e000000, v2
	v_sub_f32_e32 v2, v5, v4
	v_mov_b32_e32 v4, v10
	v_mov_b32_e32 v5, v14
	v_pk_mul_f32 v[0:1], v[4:5], v[0:1]
	v_mov_b32_e32 v10, v15
	v_add_f32_e32 v0, v0, v1
	v_mul_f32_e32 v12, 0x3e000000, v0
	v_and_b32_e32 v1, 0xffff0000, v3
	v_and_b32_e32 v0, 0xffff0000, v7
	v_mul_f32_e32 v9, 0x3e000000, v2
	v_pk_mul_f32 v[2:3], v[10:11], v[0:1]
	v_mov_b32_e32 v14, v11
	v_sub_f32_e32 v2, v3, v2
	v_mul_f32_e32 v3, 0x3e000000, v2
	v_cvt_pk_bf16_f32 v2, v19, v6
	v_cvt_pk_bf16_f32 v6, v20, v8
	v_or_b32_e32 v8, s22, v68
	v_pk_mul_f32 v[0:1], v[14:15], v[0:1]
	v_cvt_pk_bf16_f32 v3, v9, v3
	v_cvt_pk_bf16_f32 v5, v16, v18
	v_mad_u64_u32 v[8:9], s[26:27], v8, s5, v[44:45]
	v_or_b32_e32 v16, s15, v68
	v_add_f32_e32 v0, v0, v1
	v_cvt_pk_bf16_f32 v1, v25, v17
	v_mad_i32_i24 v9, s21, v207, v9
	v_ashrrev_i32_e32 v17, 31, v16
	v_mul_f32_e32 v7, 0x3e000000, v0
	v_lshl_add_u64 v[8:9], v[8:9], 0, s[36:37]
	v_lshlrev_b64 v[16:17], 7, v[16:17]
	v_cvt_pk_bf16_f32 v0, v28, v26
	v_cvt_pk_bf16_f32 v4, v29, v24
	v_cvt_pk_bf16_f32 v7, v12, v7
	v_lshl_add_u64 v[12:13], v[8:9], 0, v[86:87]
	v_lshl_add_u64 v[20:21], v[64:65], 0, v[16:17]
	v_lshl_add_u64 v[28:29], v[66:67], 0, v[16:17]
	global_load_dwordx4 v[8:11], v[12:13], off offset:3584
	s_nop 0
	global_load_dwordx4 v[12:15], v[12:13], off offset:3648
	s_nop 0
	global_load_dwordx4 v[16:19], v[20:21], off offset:16
	global_load_dwordx4 v[24:27], v[20:21], off
	s_nop 0
	global_load_dwordx4 v[20:23], v[28:29], off offset:16
	s_nop 0
	global_load_dwordx4 v[28:31], v[28:29], off
	s_waitcnt vmcnt(5)
	v_lshlrev_b32_e32 v35, 16, v8
	s_waitcnt vmcnt(4)
	v_lshlrev_b32_e32 v34, 16, v12
	s_waitcnt vmcnt(0)
; __device__ __forceinline__ unsigned pk2(float lo, float hi) { unsigned r; asm("v_cvt_pk_bf16_f32 %0, %1, %2" : "=v"(r) : "v"(lo), "v"(hi)); return r; }
; __device__ __forceinline__ float bflo(unsigned u) { return __uint_as_float(u << 16); }
; __device__ __forceinline__ float bfhi(unsigned u) { return __uint_as_float(u & 0xffff0000u); }
; __device__ __forceinline__ void rot8(u32x4 x1, u32x4 x2, const float* cs, const float* sn, float sc, u32x4& o1, u32x4& o2) {
;     const f32x4 c0 = *(const f32x4*)cs, c1 = *(const f32x4*)(cs + 4), s0 = *(const f32x4*)sn, s1 = *(const f32x4*)(sn + 4);
;     float a[8], b[8], c[8], s[8];
;     a[0] = bflo(x1.x); a[1] = bfhi(x1.x); a[2] = bflo(x1.y); a[3] = bfhi(x1.y); a[4] = bflo(x1.z); a[5] = bfhi(x1.z); a[6] = bflo(x1.w); a[7] = bfhi(x1.w);
;     b[0] = bflo(x2.x); b[1] = bfhi(x2.x); b[2] = bflo(x2.y); b[3] = bfhi(x2.y); b[4] = bflo(x2.z); b[5] = bfhi(x2.z); b[6] = bflo(x2.w); b[7] = bfhi(x2.w);
; #pragma unroll
;     for (int i = 0; i < 4; ++i) { c[i] = c0[i]; c[4 + i] = c1[i]; s[i] = s0[i]; s[4 + i] = s1[i]; }
;     float p[8], q[8];
; #pragma unroll
;     for (int i = 0; i < 8; ++i) { p[i] = (a[i] * c[i] - b[i] * s[i]) * sc; q[i] = (a[i] * s[i] + b[i] * c[i]) * sc; }
;     o1.x = pk2(p[0], p[1]); o1.y = pk2(p[2], p[3]); o1.z = pk2(p[4], p[5]); o1.w = pk2(p[6], p[7]);
;     o2.x = pk2(q[0], q[1]); o2.y = pk2(q[2], q[3]); o2.z = pk2(q[4], q[5]); o2.w = pk2(q[6], q[7]);
; }
; __device__ __forceinline__ void retout_item(const bf16_t* hbuf, const float* rot, const float* kvbuf, const float* normg, bf16_t* mixed, LAS bf16_t* vT, int item, int lane) {
;     ...
;     for (int mt = 0; mt < 4; ++mt) { const int row = 16 * mt + r; const bf16_t* kp = hbuf + (t0 + row) * INWP + C_RK + h * 64 + 8 * q; const int pos = n * 64 + row; u32x4 o1, o2;
;         rot8(*(const u32x4*)kp, *(const u32x4*)(kp + 32), cs + (size_t)pos * 32 + 8 * q, sn + (size_t)pos * 32 + 8 * q, 0.125f, o1, o2); kf[mt][0] = as_bf16x8(o1); kf[mt][1] = as_bf16x8(o2); }
	v_mov_b32_e32 v36, v28
	v_mov_b32_e32 v37, v24
	v_pk_mul_f32 v[36:37], v[36:37], v[34:35]
	s_nop 0
	v_sub_f32_e32 v36, v37, v36
	v_mul_f32_e32 v40, 0x3e000000, v36
	v_mov_b32_e32 v36, v24
	v_mov_b32_e32 v37, v28
	v_pk_mul_f32 v[34:35], v[36:37], v[34:35]
	v_mov_b32_e32 v28, v25
	v_add_f32_e32 v24, v34, v35
	v_mul_f32_e32 v41, 0x3e000000, v24
	v_and_b32_e32 v35, 0xffff0000, v8
	v_and_b32_e32 v34, 0xffff0000, v12
	v_mov_b32_e32 v24, v29
	v_pk_mul_f32 v[36:37], v[24:25], v[34:35]
	v_pk_mul_f32 v[24:25], v[28:29], v[34:35]
	v_sub_f32_e32 v8, v37, v36
	v_mul_f32_e32 v36, 0x3e000000, v8
	v_add_f32_e32 v8, v24, v25
	v_lshlrev_b32_e32 v25, 16, v9
	v_lshlrev_b32_e32 v24, 16, v13
	v_mov_b32_e32 v28, v30
	v_mov_b32_e32 v29, v26
	v_pk_mul_f32 v[28:29], v[28:29], v[24:25]
	v_mul_f32_e32 v34, 0x3e000000, v8
	v_sub_f32_e32 v8, v29, v28
	v_mov_b32_e32 v28, v26
	v_mov_b32_e32 v29, v30
	v_pk_mul_f32 v[24:25], v[28:29], v[24:25]
	v_mul_f32_e32 v35, 0x3e000000, v8
	v_add_f32_e32 v8, v24, v25
	v_mul_f32_e32 v24, 0x3e000000, v8
	v_and_b32_e32 v9, 0xffff0000, v9
	v_and_b32_e32 v8, 0xffff0000, v13
	v_mov_b32_e32 v26, v31
	v_mov_b32_e32 v30, v27
	v_pk_mul_f32 v[12:13], v[26:27], v[8:9]
	v_pk_mul_f32 v[8:9], v[30:31], v[8:9]
	v_sub_f32_e32 v12, v13, v12
	v_add_f32_e32 v8, v8, v9
	v_mul_f32_e32 v25, 0x3e000000, v12
	v_mul_f32_e32 v26, 0x3e000000, v8
	v_lshlrev_b32_e32 v9, 16, v10
	v_lshlrev_b32_e32 v8, 16, v14
	v_mov_b32_e32 v12, v20
	v_mov_b32_e32 v13, v16
	v_pk_mul_f32 v[12:13], v[12:13], v[8:9]
	s_nop 0
	v_sub_f32_e32 v12, v13, v12
	v_mul_f32_e32 v27, 0x3e000000, v12
	v_mov_b32_e32 v12, v16
	v_mov_b32_e32 v13, v20
	v_pk_mul_f32 v[8:9], v[12:13], v[8:9]
	v_mov_b32_e32 v16, v21
	v_add_f32_e32 v8, v8, v9
	v_mul_f32_e32 v28, 0x3e000000, v8
	v_and_b32_e32 v9, 0xffff0000, v10
	v_and_b32_e32 v8, 0xffff0000, v14
	v_mov_b32_e32 v20, v17
	v_pk_mul_f32 v[12:13], v[16:17], v[8:9]
	v_pk_mul_f32 v[8:9], v[20:21], v[8:9]
	v_sub_f32_e32 v10, v13, v12
	v_add_f32_e32 v8, v8, v9
	v_mul_f32_e32 v16, 0x3e000000, v8
	v_lshlrev_b32_e32 v9, 16, v11
	v_lshlrev_b32_e32 v8, 16, v15
	v_mov_b32_e32 v12, v22
	v_mov_b32_e32 v13, v18
	v_pk_mul_f32 v[12:13], v[12:13], v[8:9]
	v_mul_f32_e32 v14, 0x3e000000, v10
	v_sub_f32_e32 v10, v13, v12
	v_mov_b32_e32 v12, v18
	v_mov_b32_e32 v13, v22
	v_pk_mul_f32 v[8:9], v[12:13], v[8:9]
	v_mov_b32_e32 v18, v23
	v_add_f32_e32 v8, v8, v9
	v_mul_f32_e32 v20, 0x3e000000, v8
	v_and_b32_e32 v9, 0xffff0000, v11
	v_and_b32_e32 v8, 0xffff0000, v15
	v_mul_f32_e32 v17, 0x3e000000, v10
	v_pk_mul_f32 v[10:11], v[18:19], v[8:9]
	v_mov_b32_e32 v22, v19
	v_sub_f32_e32 v10, v11, v10
	v_mul_f32_e32 v11, 0x3e000000, v10
	v_cvt_pk_bf16_f32 v10, v27, v14
	v_cvt_pk_bf16_f32 v14, v28, v16
	v_or_b32_e32 v16, s22, v70
	v_pk_mul_f32 v[8:9], v[22:23], v[8:9]
	v_cvt_pk_bf16_f32 v11, v17, v11
	v_cvt_pk_bf16_f32 v13, v24, v26
	v_mad_u64_u32 v[16:17], s[26:27], v16, s5, v[44:45]
	v_or_b32_e32 v24, s15, v70
	v_add_f32_e32 v8, v8, v9
	v_cvt_pk_bf16_f32 v9, v35, v25
	v_mad_i32_i24 v17, s21, v207, v17
	v_ashrrev_i32_e32 v25, 31, v24
	v_mul_f32_e32 v15, 0x3e000000, v8
	v_lshl_add_u64 v[16:17], v[16:17], 0, s[36:37]
	v_lshlrev_b64 v[24:25], 7, v[24:25]
	v_cvt_pk_bf16_f32 v8, v40, v36
	v_cvt_pk_bf16_f32 v12, v41, v34
	v_cvt_pk_bf16_f32 v15, v20, v15
	v_lshl_add_u64 v[20:21], v[16:17], 0, v[86:87]
	v_lshl_add_u64 v[28:29], v[64:65], 0, v[24:25]
	v_lshl_add_u64 v[40:41], v[66:67], 0, v[24:25]
	global_load_dwordx4 v[16:19], v[20:21], off offset:3584
	s_nop 0
	global_load_dwordx4 v[20:23], v[20:21], off offset:3648
	s_nop 0
	global_load_dwordx4 v[24:27], v[28:29], off offset:16
	global_load_dwordx4 v[34:37], v[28:29], off
	s_nop 0
	global_load_dwordx4 v[28:31], v[40:41], off offset:16
	s_nop 0
	global_load_dwordx4 v[40:43], v[40:41], off
	s_waitcnt vmcnt(5)
	v_lshlrev_b32_e32 v47, 16, v16
	s_waitcnt vmcnt(4)
	v_lshlrev_b32_e32 v46, 16, v20
	s_waitcnt vmcnt(0)
	v_mov_b32_e32 v48, v40
	v_mov_b32_e32 v49, v34
	v_pk_mul_f32 v[48:49], v[48:49], v[46:47]
	s_nop 0
	v_sub_f32_e32 v48, v49, v48
	v_mul_f32_e32 v50, 0x3e000000, v48
	v_mov_b32_e32 v48, v34
	v_mov_b32_e32 v49, v40
	v_pk_mul_f32 v[46:47], v[48:49], v[46:47]
	v_mov_b32_e32 v40, v35
	v_add_f32_e32 v34, v46, v47
	v_mul_f32_e32 v51, 0x3e000000, v34
	v_and_b32_e32 v47, 0xffff0000, v16
	v_and_b32_e32 v46, 0xffff0000, v20
	v_mov_b32_e32 v34, v41
	v_pk_mul_f32 v[48:49], v[34:35], v[46:47]
	v_pk_mul_f32 v[34:35], v[40:41], v[46:47]
	v_sub_f32_e32 v16, v49, v48
	v_mul_f32_e32 v48, 0x3e000000, v16
	v_add_f32_e32 v16, v34, v35
	v_lshlrev_b32_e32 v35, 16, v17
	v_lshlrev_b32_e32 v34, 16, v21
	v_mov_b32_e32 v40, v42
	v_mov_b32_e32 v41, v36
	v_pk_mul_f32 v[40:41], v[40:41], v[34:35]
	v_mul_f32_e32 v46, 0x3e000000, v16
	v_sub_f32_e32 v16, v41, v40
	v_mov_b32_e32 v40, v36
	v_mov_b32_e32 v41, v42
	v_pk_mul_f32 v[34:35], v[40:41], v[34:35]
	v_mul_f32_e32 v47, 0x3e000000, v16
	v_add_f32_e32 v16, v34, v35
	v_mul_f32_e32 v34, 0x3e000000, v16
	v_and_b32_e32 v17, 0xffff0000, v17
	v_and_b32_e32 v16, 0xffff0000, v21
	v_mov_b32_e32 v36, v43
	v_mov_b32_e32 v42, v37
	v_pk_mul_f32 v[20:21], v[36:37], v[16:17]
	v_pk_mul_f32 v[16:17], v[42:43], v[16:17]
	v_sub_f32_e32 v20, v21, v20
	v_add_f32_e32 v16, v16, v17
	v_mul_f32_e32 v35, 0x3e000000, v20
	v_mul_f32_e32 v36, 0x3e000000, v16
	v_lshlrev_b32_e32 v17, 16, v18
	v_lshlrev_b32_e32 v16, 16, v22
	v_mov_b32_e32 v20, v28
	v_mov_b32_e32 v21, v24
	v_pk_mul_f32 v[20:21], v[20:21], v[16:17]
	s_nop 0
	v_sub_f32_e32 v20, v21, v20
	v_mul_f32_e32 v37, 0x3e000000, v20
	v_mov_b32_e32 v20, v24
	v_mov_b32_e32 v21, v28
	v_pk_mul_f32 v[16:17], v[20:21], v[16:17]
	v_mov_b32_e32 v24, v29
	v_add_f32_e32 v16, v16, v17
	v_mul_f32_e32 v40, 0x3e000000, v16
; #define LAS __attribute__((address_space(3)))
; __device__ __forceinline__ unsigned pk2(float lo, float hi) { unsigned r; asm("v_cvt_pk_bf16_f32 %0, %1, %2" : "=v"(r) : "v"(lo), "v"(hi)); return r; }
; __device__ __forceinline__ void retout_item(const bf16_t* hbuf, const float* rot, const float* kvbuf, const float* normg, bf16_t* mixed, LAS bf16_t* vT, int item, int lane) {
;     ...
;     for (int mt = 0; mt < 4; ++mt) { const int row = 16 * mt + r; const bf16_t* kp = hbuf + (t0 + row) * INWP + C_RK + h * 64 + 8 * q; const int pos = n * 64 + row; u32x4 o1, o2;
;         rot8(*(const u32x4*)kp, *(const u32x4*)(kp + 32), cs + (size_t)pos * 32 + 8 * q, sn + (size_t)pos * 32 + 8 * q, 0.125f, o1, o2); kf[mt][0] = as_bf16x8(o1); kf[mt][1] = as_bf16x8(o2); }
;     const float* Rp = kvbuf + (size_t)item * 4096;
; #pragma unroll
;     for (int et = 0; et < 4; ++et)
; #pragma unroll
;         for (int ks = 0; ks < 2; ++ks) { const float* p = Rp + (16 * et + r) * 64 + 32 * ks + 8 * q; const f32x4 a = *(const f32x4*)p, c = *(const f32x4*)(p + 4);
;             *(LAS u32x4*)(RT + (16 * et + r) * TLD + 32 * ks + 8 * q) = (u32x4){pk2(a[0], a[1]), pk2(a[2], a[3]), pk2(c[0], c[1]), pk2(c[2], c[3])}; }
	v_and_b32_e32 v17, 0xffff0000, v18
	v_and_b32_e32 v16, 0xffff0000, v22
	v_mov_b32_e32 v28, v25
	v_pk_mul_f32 v[20:21], v[24:25], v[16:17]
	v_pk_mul_f32 v[16:17], v[28:29], v[16:17]
	v_sub_f32_e32 v18, v21, v20
	v_add_f32_e32 v16, v16, v17
	v_mul_f32_e32 v24, 0x3e000000, v16
	v_lshlrev_b32_e32 v17, 16, v19
	v_lshlrev_b32_e32 v16, 16, v23
	v_mov_b32_e32 v20, v30
	v_mov_b32_e32 v21, v26
	v_pk_mul_f32 v[20:21], v[20:21], v[16:17]
	v_mul_f32_e32 v22, 0x3e000000, v18
	v_sub_f32_e32 v18, v21, v20
	v_mov_b32_e32 v20, v26
	v_mov_b32_e32 v21, v30
	v_pk_mul_f32 v[16:17], v[20:21], v[16:17]
	v_mov_b32_e32 v26, v31
	v_add_f32_e32 v16, v16, v17
	v_mul_f32_e32 v28, 0x3e000000, v16
	v_and_b32_e32 v17, 0xffff0000, v19
	v_and_b32_e32 v16, 0xffff0000, v23
	v_mul_f32_e32 v25, 0x3e000000, v18
	v_pk_mul_f32 v[18:19], v[26:27], v[16:17]
	v_mov_b32_e32 v30, v27
	v_sub_f32_e32 v18, v19, v18
	v_mul_f32_e32 v19, 0x3e000000, v18
	v_cvt_pk_bf16_f32 v18, v37, v22
	v_cvt_pk_bf16_f32 v22, v40, v24
	v_or_b32_e32 v24, s22, v72
	v_pk_mul_f32 v[16:17], v[30:31], v[16:17]
	v_cvt_pk_bf16_f32 v19, v25, v19
	v_cvt_pk_bf16_f32 v21, v34, v36
	v_mad_u64_u32 v[24:25], s[22:23], v24, s5, v[44:45]
	v_or_b32_e32 v34, s15, v72
	v_add_f32_e32 v16, v16, v17
	v_cvt_pk_bf16_f32 v17, v47, v35
	v_mad_i32_i24 v25, s21, v207, v25
	v_ashrrev_i32_e32 v35, 31, v34
	v_mul_f32_e32 v23, 0x3e000000, v16
	v_lshl_add_u64 v[24:25], v[24:25], 0, s[36:37]
	v_lshlrev_b64 v[34:35], 7, v[34:35]
	v_cvt_pk_bf16_f32 v16, v50, v48
	v_cvt_pk_bf16_f32 v23, v28, v23
	v_lshl_add_u64 v[28:29], v[24:25], 0, v[86:87]
	v_lshl_add_u64 v[40:41], v[64:65], 0, v[34:35]
	v_lshl_add_u64 v[48:49], v[66:67], 0, v[34:35]
	v_cvt_pk_bf16_f32 v20, v51, v46
	global_load_dwordx4 v[24:27], v[28:29], off offset:3584
	s_nop 0
	global_load_dwordx4 v[28:31], v[28:29], off offset:3648
	s_nop 0
	global_load_dwordx4 v[34:37], v[40:41], off offset:16
	global_load_dwordx4 v[44:47], v[40:41], off
	s_nop 0
	global_load_dwordx4 v[40:43], v[48:49], off offset:16
	s_nop 0
	global_load_dwordx4 v[48:51], v[48:49], off
	s_lshl_b64 s[22:23], s[0:1], 14
	s_waitcnt vmcnt(5)
	v_lshlrev_b32_e32 v55, 16, v24
	s_waitcnt vmcnt(4)
	v_lshlrev_b32_e32 v54, 16, v28
	s_waitcnt vmcnt(0)
	v_mov_b32_e32 v56, v48
	v_mov_b32_e32 v57, v44
	v_pk_mul_f32 v[56:57], v[56:57], v[54:55]
	s_nop 0
	v_sub_f32_e32 v56, v57, v56
	v_mul_f32_e32 v58, 0x3e000000, v56
	v_mov_b32_e32 v56, v44
	v_mov_b32_e32 v57, v48
	v_pk_mul_f32 v[54:55], v[56:57], v[54:55]
	v_mov_b32_e32 v48, v45
	v_add_f32_e32 v44, v54, v55
	v_mul_f32_e32 v59, 0x3e000000, v44
	v_and_b32_e32 v55, 0xffff0000, v24
	v_and_b32_e32 v54, 0xffff0000, v28
	v_mov_b32_e32 v44, v49
	v_pk_mul_f32 v[56:57], v[44:45], v[54:55]
	v_pk_mul_f32 v[44:45], v[48:49], v[54:55]
	v_sub_f32_e32 v24, v57, v56
	v_mul_f32_e32 v56, 0x3e000000, v24
	v_add_f32_e32 v24, v44, v45
	v_lshlrev_b32_e32 v45, 16, v25
	v_lshlrev_b32_e32 v44, 16, v29
	v_mov_b32_e32 v48, v50
	v_mov_b32_e32 v49, v46
	v_pk_mul_f32 v[48:49], v[48:49], v[44:45]
	v_mul_f32_e32 v54, 0x3e000000, v24
	v_sub_f32_e32 v24, v49, v48
	v_mov_b32_e32 v48, v46
	v_mov_b32_e32 v49, v50
	v_pk_mul_f32 v[44:45], v[48:49], v[44:45]
	v_mul_f32_e32 v55, 0x3e000000, v24
	v_add_f32_e32 v24, v44, v45
	v_mul_f32_e32 v44, 0x3e000000, v24
	v_and_b32_e32 v25, 0xffff0000, v25
	v_and_b32_e32 v24, 0xffff0000, v29
	v_mov_b32_e32 v46, v51
	v_mov_b32_e32 v50, v47
	v_pk_mul_f32 v[28:29], v[46:47], v[24:25]
	v_pk_mul_f32 v[24:25], v[50:51], v[24:25]
	v_sub_f32_e32 v28, v29, v28
	v_add_f32_e32 v24, v24, v25
	v_mul_f32_e32 v45, 0x3e000000, v28
	v_mul_f32_e32 v46, 0x3e000000, v24
	v_lshlrev_b32_e32 v25, 16, v26
	v_lshlrev_b32_e32 v24, 16, v30
	v_mov_b32_e32 v28, v40
	v_mov_b32_e32 v29, v34
	v_pk_mul_f32 v[28:29], v[28:29], v[24:25]
	s_nop 0
	v_sub_f32_e32 v28, v29, v28
	v_mul_f32_e32 v47, 0x3e000000, v28
	v_mov_b32_e32 v28, v34
	v_mov_b32_e32 v29, v40
	v_pk_mul_f32 v[24:25], v[28:29], v[24:25]
	v_mov_b32_e32 v34, v41
	v_add_f32_e32 v24, v24, v25
	v_mul_f32_e32 v48, 0x3e000000, v24
	v_and_b32_e32 v25, 0xffff0000, v26
	v_and_b32_e32 v24, 0xffff0000, v30
	v_mov_b32_e32 v40, v35
	v_pk_mul_f32 v[28:29], v[34:35], v[24:25]
	v_pk_mul_f32 v[24:25], v[40:41], v[24:25]
	v_sub_f32_e32 v26, v29, v28
	v_add_f32_e32 v24, v24, v25
	v_mul_f32_e32 v34, 0x3e000000, v24
	v_lshlrev_b32_e32 v25, 16, v27
	v_lshlrev_b32_e32 v24, 16, v31
	v_mov_b32_e32 v28, v42
	v_mov_b32_e32 v29, v36
	v_pk_mul_f32 v[28:29], v[28:29], v[24:25]
	v_mul_f32_e32 v30, 0x3e000000, v26
	v_sub_f32_e32 v26, v29, v28
	v_mov_b32_e32 v28, v36
	v_mov_b32_e32 v29, v42
	v_pk_mul_f32 v[24:25], v[28:29], v[24:25]
	v_mov_b32_e32 v36, v43
	v_add_f32_e32 v24, v24, v25
	v_mul_f32_e32 v40, 0x3e000000, v24
	v_and_b32_e32 v25, 0xffff0000, v27
	v_and_b32_e32 v24, 0xffff0000, v31
	v_mul_f32_e32 v35, 0x3e000000, v26
	v_pk_mul_f32 v[26:27], v[36:37], v[24:25]
	v_mov_b32_e32 v42, v37
	v_sub_f32_e32 v26, v27, v26
	v_mul_f32_e32 v27, 0x3e000000, v26
	v_pk_mul_f32 v[24:25], v[42:43], v[24:25]
	v_cvt_pk_bf16_f32 v26, v47, v30
	v_cvt_pk_bf16_f32 v27, v35, v27
	v_cvt_pk_bf16_f32 v30, v48, v34
	v_lshl_add_u64 v[34:35], v[74:75], 0, s[22:23]
	v_add_f32_e32 v24, v24, v25
	v_mul_f32_e32 v31, 0x3e000000, v24
	v_cvt_pk_bf16_f32 v25, v55, v45
	v_cvt_pk_bf16_f32 v29, v44, v46
	v_cvt_pk_bf16_f32 v31, v40, v31
	v_lshl_add_u64 v[144:145], v[34:35], 0, v[88:89]
	v_lshl_add_u64 v[146:147], v[34:35], 0, v[90:91]
	v_lshl_add_u64 v[148:149], v[34:35], 0, v[92:93]
	v_lshl_add_u64 v[150:151], v[34:35], 0, v[94:95]
	global_load_dwordx4 v[172:175], v[144:145], off
	global_load_dwordx4 v[176:179], v[144:145], off offset:16
	global_load_dwordx4 v[180:183], v[144:145], off offset:128
	global_load_dwordx4 v[184:187], v[144:145], off offset:144
	global_load_dwordx4 v[188:191], v[146:147], off
	global_load_dwordx4 v[192:195], v[146:147], off offset:16
	global_load_dwordx4 v[196:199], v[146:147], off offset:128
	global_load_dwordx4 v[200:203], v[146:147], off offset:144
	global_load_dwordx4 v[212:215], v[148:149], off
	global_load_dwordx4 v[216:219], v[148:149], off offset:16
	global_load_dwordx4 v[220:223], v[148:149], off offset:128
	global_load_dwordx4 v[224:227], v[148:149], off offset:144
	global_load_dwordx4 v[152:155], v[150:151], off
	global_load_dwordx4 v[156:159], v[150:151], off offset:16
	global_load_dwordx4 v[160:163], v[150:151], off offset:128
	global_load_dwordx4 v[232:235], v[150:151], off offset:144
	s_and_b64 s[22:23], vcc, exec
	s_cselect_b32 s1, 32, 0
	v_ldexp_f32 v34, v53, s1
	v_log_f32_e32 v34, v34
	s_waitcnt vmcnt(14)
; #define LAS __attribute__((address_space(3)))
; __device__ __forceinline__ unsigned pk2(float lo, float hi) { unsigned r; asm("v_cvt_pk_bf16_f32 %0, %1, %2" : "=v"(r) : "v"(lo), "v"(hi)); return r; }
; __device__ __forceinline__ void lds_fence() { asm volatile("s_waitcnt lgkmcnt(0)" ::: "memory"); }
; __device__ __forceinline__ void retout_item(const bf16_t* hbuf, const float* rot, const float* kvbuf, const float* normg, bf16_t* mixed, LAS bf16_t* vT, int item, int lane) {
;     ...
;         for (int ks = 0; ks < 2; ++ks) { const float* p = Rp + (16 * et + r) * 64 + 32 * ks + 8 * q; const f32x4 a = *(const f32x4*)p, c = *(const f32x4*)(p + 4);
;             *(LAS u32x4*)(RT + (16 * et + r) * TLD + 32 * ks + 8 * q) = (u32x4){pk2(a[0], a[1]), pk2(a[2], a[3]), pk2(c[0], c[1]), pk2(c[2], c[3])}; }
;     lds_fence();
; #pragma unroll 1
;     for (int ct = 0; ct < 4; ++ct) {
;         const int c = 16 * ct + r; const bf16_t* qp = hbuf + (t0 + c) * INWP + C_RQ + h * 64 + 8 * q; const int pos = n * 64 + c; u32x4 o1, o2;
;         rot8(*(const u32x4*)qp, *(const u32x4*)(qp + 32), cs + (size_t)pos * 32 + 8 * q, sn + (size_t)pos * 32 + 8 * q, 1.0f, o1, o2);
;         const bf16x8 q0 = as_bf16x8(o1), q1 = as_bf16x8(o2);
;         f32x4 OT[4];
;         const float xi = __builtin_amdgcn_exp2f(l2g * (float)(c + 1));
; #pragma unroll
;         for (int et = 0; et < 4; ++et) { f32x4 acc = {0.f, 0.f, 0.f, 0.f};
;             const bf16x8 R0 = *(const LAS bf16x8*)(RT + (16 * et + r) * TLD + 8 * q), R1 = *(const LAS bf16x8*)(RT + (16 * et + r) * TLD + 32 + 8 * q);
;             acc = __builtin_amdgcn_mfma_f32_16x16x32_bf16(R0, q0, acc, 0, 0, 0); acc = __builtin_amdgcn_mfma_f32_16x16x32_bf16(R1, q1, acc, 0, 0, 0);
	v_cvt_pk_bf16_f32 v172, v172, v173
	v_cvt_pk_bf16_f32 v173, v174, v175
	v_cvt_pk_bf16_f32 v174, v176, v177
	v_cvt_pk_bf16_f32 v175, v178, v179
	ds_write_b128 v63, v[172:175] offset:9216
	s_waitcnt vmcnt(12)
	v_cvt_pk_bf16_f32 v180, v180, v181
	v_cvt_pk_bf16_f32 v181, v182, v183
	v_cvt_pk_bf16_f32 v182, v184, v185
	v_cvt_pk_bf16_f32 v183, v186, v187
	ds_write_b128 v63, v[180:183] offset:9280
	s_waitcnt vmcnt(10)
	v_cvt_pk_bf16_f32 v188, v188, v189
	v_cvt_pk_bf16_f32 v189, v190, v191
	v_cvt_pk_bf16_f32 v190, v192, v193
	v_cvt_pk_bf16_f32 v191, v194, v195
	ds_write_b128 v63, v[188:191] offset:11520
	s_waitcnt vmcnt(8)
	v_cvt_pk_bf16_f32 v196, v196, v197
	v_cvt_pk_bf16_f32 v197, v198, v199
	v_cvt_pk_bf16_f32 v198, v200, v201
	v_cvt_pk_bf16_f32 v199, v202, v203
	ds_write_b128 v63, v[196:199] offset:11584
	s_waitcnt vmcnt(6)
	v_cvt_pk_bf16_f32 v212, v212, v213
	v_cvt_pk_bf16_f32 v213, v214, v215
	v_cvt_pk_bf16_f32 v214, v216, v217
	v_cvt_pk_bf16_f32 v215, v218, v219
	ds_write_b128 v63, v[212:215] offset:13824
	s_waitcnt vmcnt(4)
	v_cvt_pk_bf16_f32 v220, v220, v221
	v_cvt_pk_bf16_f32 v221, v222, v223
	v_cvt_pk_bf16_f32 v222, v224, v225
	v_cvt_pk_bf16_f32 v223, v226, v227
	ds_write_b128 v63, v[220:223] offset:13888
	s_waitcnt vmcnt(2)
	v_cvt_pk_bf16_f32 v152, v152, v153
	v_cvt_pk_bf16_f32 v153, v154, v155
	v_cvt_pk_bf16_f32 v154, v156, v157
	v_cvt_pk_bf16_f32 v155, v158, v159
	ds_write_b128 v128, v[152:155] offset:9216
	s_waitcnt vmcnt(0)
	v_cvt_pk_bf16_f32 v160, v160, v161
	v_cvt_pk_bf16_f32 v161, v162, v163
	v_cvt_pk_bf16_f32 v162, v232, v233
	v_cvt_pk_bf16_f32 v163, v234, v235
	ds_write_b128 v128, v[160:163] offset:9280
	v_cndmask_b32_e32 v35, 0, v246, vcc
	v_sub_f32_e32 v85, v34, v35
	s_waitcnt lgkmcnt(0)
	v_lshl_or_b32 v34, s0, 6, v60
	s_lshl_b32 s1, s17, 14
	v_mov_b32_e32 v53, s21
	v_subrev_u32_e32 v87, s1, v34
	v_mad_u64_u32 v[98:99], s[22:23], v52, s5, v[78:79]
	v_mad_u64_u32 v[100:101], s[22:23], v52, s5, v[80:81]
	v_lshlrev_b64 v[34:35], 11, v[52:53]
	v_mad_i32_i24 v99, s21, v207, v99
	v_mad_i32_i24 v101, s21, v207, v101
	v_lshl_add_u64 v[102:103], v[82:83], 0, v[34:35]
	v_mov_b32_e32 v91, v126
	v_cvt_pk_bf16_f32 v24, v58, v56
	v_cvt_pk_bf16_f32 v28, v59, v54
.LBB0_176:
	v_add_u32_e32 v44, s12, v87
	v_lshl_add_u64 v[34:35], v[100:101], 0, s[36:37]
	v_ashrrev_i32_e32 v45, 31, v44
	v_add_co_u32_e32 v40, vcc, 0x1d408000, v34
	v_lshlrev_b64 v[44:45], 7, v[44:45]
	s_nop 0
	v_addc_co_u32_e32 v41, vcc, 0, v35, vcc
	v_lshl_add_u64 v[48:49], v[64:65], 0, v[44:45]
	v_lshl_add_u64 v[56:57], v[66:67], 0, v[44:45]
	global_load_dwordx4 v[34:37], v[40:41], off offset:2816
	s_nop 0
	global_load_dwordx4 v[40:43], v[40:41], off offset:2880
	s_nop 0
	global_load_dwordx4 v[44:47], v[48:49], off offset:16
	s_nop 0
	global_load_dwordx4 v[48:51], v[48:49], off
	s_nop 0
	global_load_dwordx4 v[52:55], v[56:57], off offset:16
	s_nop 0
	global_load_dwordx4 v[56:59], v[56:57], off
	v_add_u32_e32 v93, s12, v60
	v_cmp_gt_u32_e32 vcc, v93, v61
	v_subrev_u32_e32 v141, 19, v91
	s_mov_b64 s[20:21], 0x8000
	v_lshl_add_u64 v[100:101], v[100:101], 0, s[10:11]
	s_waitcnt vmcnt(5)
	v_lshlrev_b32_e32 v131, 16, v34
	s_waitcnt vmcnt(4)
	v_lshlrev_b32_e32 v130, 16, v40
	s_waitcnt vmcnt(0)
	v_mov_b32_e32 v132, v56
	v_mov_b32_e32 v133, v48
	v_pk_mul_f32 v[132:133], v[132:133], v[130:131]
	s_nop 0
	v_sub_f32_e32 v89, v133, v132
	v_mov_b32_e32 v132, v48
	v_mov_b32_e32 v133, v56
	v_pk_mul_f32 v[130:131], v[132:133], v[130:131]
	v_mov_b32_e32 v48, v57
	v_add_f32_e32 v95, v130, v131
	v_and_b32_e32 v131, 0xffff0000, v34
	v_and_b32_e32 v130, 0xffff0000, v40
	v_mov_b32_e32 v56, v49
	v_pk_mul_f32 v[132:133], v[48:49], v[130:131]
	v_pk_mul_f32 v[48:49], v[56:57], v[130:131]
	v_mov_b32_e32 v56, v58
	v_add_f32_e32 v130, v48, v49
	v_lshlrev_b32_e32 v49, 16, v35
	v_lshlrev_b32_e32 v48, 16, v41
	v_mov_b32_e32 v57, v50
	v_pk_mul_f32 v[56:57], v[56:57], v[48:49]
	v_and_b32_e32 v35, 0xffff0000, v35
	v_sub_f32_e32 v131, v57, v56
	v_mov_b32_e32 v56, v50
	v_mov_b32_e32 v57, v58
	v_and_b32_e32 v34, 0xffff0000, v41
	v_mov_b32_e32 v50, v59
	v_mov_b32_e32 v58, v51
	v_pk_mul_f32 v[48:49], v[56:57], v[48:49]
	v_pk_mul_f32 v[40:41], v[50:51], v[34:35]
	v_pk_mul_f32 v[34:35], v[58:59], v[34:35]
	v_add_f32_e32 v48, v48, v49
	v_sub_f32_e32 v49, v41, v40
	v_add_f32_e32 v50, v34, v35
	v_lshlrev_b32_e32 v35, 16, v36
	v_lshlrev_b32_e32 v34, 16, v42
	v_mov_b32_e32 v40, v52
	v_mov_b32_e32 v41, v44
	v_pk_mul_f32 v[40:41], v[40:41], v[34:35]
	v_sub_f32_e32 v129, v133, v132
	v_sub_f32_e32 v51, v41, v40
	v_mov_b32_e32 v40, v44
	v_mov_b32_e32 v41, v52
	v_pk_mul_f32 v[34:35], v[40:41], v[34:35]
	v_mov_b32_e32 v44, v53
	v_add_f32_e32 v56, v34, v35
	v_and_b32_e32 v35, 0xffff0000, v36
	v_and_b32_e32 v34, 0xffff0000, v42
	v_mov_b32_e32 v52, v45
	v_pk_mul_f32 v[40:41], v[44:45], v[34:35]
	v_pk_mul_f32 v[34:35], v[52:53], v[34:35]
	v_sub_f32_e32 v42, v41, v40
	v_add_f32_e32 v44, v34, v35
	v_lshlrev_b32_e32 v35, 16, v37
	v_lshlrev_b32_e32 v34, 16, v43
	v_mov_b32_e32 v40, v54
	v_mov_b32_e32 v41, v46
	v_pk_mul_f32 v[40:41], v[40:41], v[34:35]
	s_nop 0
	v_sub_f32_e32 v45, v41, v40
	v_mov_b32_e32 v40, v46
	v_mov_b32_e32 v41, v54
	v_pk_mul_f32 v[34:35], v[40:41], v[34:35]
	v_mov_b32_e32 v46, v55
	v_add_f32_e32 v52, v34, v35
	v_and_b32_e32 v35, 0xffff0000, v37
	v_and_b32_e32 v34, 0xffff0000, v43
	v_mov_b32_e32 v54, v47
	v_pk_mul_f32 v[36:37], v[46:47], v[34:35]
	v_pk_mul_f32 v[34:35], v[54:55], v[34:35]
	v_sub_f32_e32 v37, v37, v36
	v_add_f32_e32 v43, v34, v35
	v_cvt_pk_bf16_f32 v35, v131, v49
	v_cvt_pk_bf16_f32 v36, v51, v42
	v_cvt_pk_bf16_f32 v41, v48, v50
	v_cvt_pk_bf16_f32 v43, v52, v43
	ds_read_b128 v[46:49], v104 offset:9216
	ds_read_b128 v[50:53], v104 offset:9280
	v_cvt_pk_bf16_f32 v42, v56, v44
	v_add_u32_e32 v44, 1, v93
	v_cvt_f32_u32_e32 v44, v44
	v_cvt_pk_bf16_f32 v34, v89, v129
	v_cvt_pk_bf16_f32 v37, v45, v37
	v_cvt_pk_bf16_f32 v40, v95, v130
	v_mul_f32_e32 v44, v85, v44
	s_waitcnt lgkmcnt(1)
; #define LAS __attribute__((address_space(3)))
; __device__ __forceinline__ bf16x8 pack_tiles(const f32x4& t0, const f32x4& t1) { u32x4 w; w.x = pk2(t0[0], t0[1]); w.y = pk2(t0[2], t0[3]); w.z = pk2(t1[0], t1[1]); w.w = pk2(t1[2], t1[3]); return as_bf16x8(w); }
; __device__ __forceinline__ void retout_item(const bf16_t* hbuf, const float* rot, const float* kvbuf, const float* normg, bf16_t* mixed, LAS bf16_t* vT, int item, int lane) {
;     ...
;         const float xi = __builtin_amdgcn_exp2f(l2g * (float)(c + 1));
; #pragma unroll
;         for (int et = 0; et < 4; ++et) { f32x4 acc = {0.f, 0.f, 0.f, 0.f};
;             const bf16x8 R0 = *(const LAS bf16x8*)(RT + (16 * et + r) * TLD + 8 * q), R1 = *(const LAS bf16x8*)(RT + (16 * et + r) * TLD + 32 + 8 * q);
;             acc = __builtin_amdgcn_mfma_f32_16x16x32_bf16(R0, q0, acc, 0, 0, 0); acc = __builtin_amdgcn_mfma_f32_16x16x32_bf16(R1, q1, acc, 0, 0, 0);
;             OT[et] = acc * xi; }
;         f32x4 st[4];
; #pragma unroll
;         for (int mt = 0; mt < 4; ++mt) { f32x4 acc = {0.f, 0.f, 0.f, 0.f};
;             acc = __builtin_amdgcn_mfma_f32_16x16x32_bf16(kf[mt][0], q0, acc, 0, 0, 0); acc = __builtin_amdgcn_mfma_f32_16x16x32_bf16(kf[mt][1], q1, acc, 0, 0, 0);
; #pragma unroll
;             for (int j = 0; j < 4; ++j) { const int m = 16 * mt + 4 * q + j; const int dd = c > m ? c - m : m - c; acc[j] *= __builtin_amdgcn_exp2f(l2g * (float)dd); }
;             st[mt] = acc; }
;         const bf16x8 p0 = pack_tiles(st[0], st[1]), p1 = pack_tiles(st[2], st[3]);
; #pragma unroll
;         for (int et = 0; et < 4; ++et) { OT[et] = __builtin_amdgcn_mfma_f32_16x16x32_bf16(vt_frag(vT, et, 0, r, q), p0, OT[et], 0, 0, 0);
;             OT[et] = __builtin_amdgcn_mfma_f32_16x16x32_bf16(vt_frag(vT, et, 1, r, q), p1, OT[et], 0, 0, 0); }
	v_mfma_f32_16x16x32_bf16 v[46:49], v[46:49], v[34:37], 0
	v_exp_f32_e32 v44, v44
	v_add_u32_e32 v129, s12, v127
	v_subrev_u32_e32 v89, 51, v91
	s_waitcnt lgkmcnt(0)
	v_mfma_f32_16x16x32_bf16 v[46:49], v[50:53], v[40:43], v[46:49]
	v_cndmask_b32_e32 v89, v89, v129, vcc
	v_cvt_f32_u32_e32 v89, v89
	v_cmp_gt_u32_e32 vcc, v93, v111
	s_add_i32 s12, s12, 16
	s_cmp_lg_u32 s12, 64
	s_nop 2
	v_pk_mul_f32 v[58:59], v[44:45], v[48:49] op_sel_hi:[0,1]
	v_pk_mul_f32 v[56:57], v[44:45], v[46:47] op_sel_hi:[0,1]
	ds_read_b128 v[46:49], v106 offset:9216
	ds_read_b128 v[50:53], v106 offset:9280
	s_waitcnt lgkmcnt(1)
	v_mfma_f32_16x16x32_bf16 v[46:49], v[46:49], v[34:37], 0
	v_mul_f32_e32 v89, v85, v89
	v_exp_f32_e32 v89, v89
	s_waitcnt lgkmcnt(0)
	v_mfma_f32_16x16x32_bf16 v[46:49], v[50:53], v[40:43], v[46:49]
	s_nop 7
	v_pk_mul_f32 v[54:55], v[44:45], v[48:49] op_sel_hi:[0,1]
	v_pk_mul_f32 v[52:53], v[44:45], v[46:47] op_sel_hi:[0,1]
	ds_read_b128 v[46:49], v108 offset:9216
	ds_read_b128 v[130:133], v108 offset:9280
	s_waitcnt lgkmcnt(1)
	v_mfma_f32_16x16x32_bf16 v[46:49], v[46:49], v[34:37], 0
	s_waitcnt lgkmcnt(0)
	v_mfma_f32_16x16x32_bf16 v[46:49], v[130:133], v[40:43], v[46:49]
	ds_read_b128 v[130:133], v110 offset:9216
	ds_read_b128 v[134:137], v110 offset:9280
	s_waitcnt lgkmcnt(1)
	v_mfma_f32_16x16x32_bf16 v[130:133], v[130:133], v[34:37], 0
	s_nop 3
	v_mul_f32_e64 v50, v44, v48
	v_mul_f32_e64 v51, v44, v49
	v_pk_mul_f32 v[48:49], v[44:45], v[46:47] op_sel_hi:[0,1]
	s_waitcnt lgkmcnt(0)
	v_mfma_f32_16x16x32_bf16 v[130:133], v[134:137], v[40:43], v[130:133]
	v_subrev_u32_e32 v137, 35, v91
	s_nop 6
	v_pk_mul_f32 v[46:47], v[44:45], v[132:133] op_sel_hi:[0,1]
	v_pk_mul_f32 v[44:45], v[44:45], v[130:131] op_sel_hi:[0,1]
	v_mfma_f32_16x16x32_bf16 v[130:133], v[0:3], v[34:37], 0
	v_mfma_f32_16x16x32_bf16 v[130:133], v[4:7], v[40:43], v[130:133]
	s_nop 7
	v_mul_f32_e32 v95, v89, v130
	v_add_u32_e32 v89, -1, v129
	v_subrev_u32_e32 v130, 50, v91
	v_cndmask_b32_e32 v89, v130, v89, vcc
	v_cvt_f32_u32_e32 v89, v89
	v_cmp_gt_u32_e32 vcc, v93, v112
	v_mul_f32_e32 v89, v85, v89
	v_exp_f32_e32 v89, v89
	s_nop 0
	v_mul_f32_e32 v130, v89, v131
	v_add_u32_e32 v89, -2, v129
	v_subrev_u32_e32 v131, 49, v91
	v_cndmask_b32_e32 v89, v131, v89, vcc
	v_cvt_f32_u32_e32 v89, v89
	v_cmp_gt_u32_e32 vcc, v93, v113
	v_cvt_pk_bf16_f32 v130, v95, v130
	v_mul_f32_e32 v89, v85, v89
	v_exp_f32_e32 v89, v89
	s_nop 0
	v_mul_f32_e32 v131, v89, v132
	v_add_u32_e32 v89, -3, v129
	v_subrev_u32_e32 v132, 48, v91
	v_cndmask_b32_e32 v89, v132, v89, vcc
	v_cvt_f32_u32_e32 v89, v89
	v_cmp_gt_u32_e32 vcc, v93, v114
	v_mul_f32_e32 v89, v85, v89
	v_exp_f32_e32 v89, v89
	s_nop 0
	v_mul_f32_e32 v136, v89, v133
	v_add_u32_e32 v89, -16, v129
	v_cndmask_b32_e32 v89, v137, v89, vcc
	v_cvt_f32_u32_e32 v89, v89
	v_mfma_f32_16x16x32_bf16 v[132:135], v[8:11], v[34:37], 0
	v_cmp_gt_u32_e32 vcc, v93, v115
	v_cvt_pk_bf16_f32 v131, v131, v136
	v_mul_f32_e32 v89, v85, v89
	v_mfma_f32_16x16x32_bf16 v[132:135], v[12:15], v[40:43], v[132:135]
	v_exp_f32_e32 v89, v89
	s_nop 6
	v_mul_f32_e32 v137, v89, v132
	v_subrev_u32_e32 v89, 17, v129
	v_subrev_u32_e32 v132, 34, v91
	v_cndmask_b32_e32 v89, v132, v89, vcc
	v_cvt_f32_u32_e32 v89, v89
	v_cmp_gt_u32_e32 vcc, v93, v116
	v_subrev_u32_e32 v132, 33, v91
	v_mul_f32_e32 v89, v85, v89
	v_exp_f32_e32 v89, v89
	s_nop 0
	v_mul_f32_e32 v138, v89, v133
	v_subrev_u32_e32 v89, 18, v129
	v_cndmask_b32_e32 v89, v132, v89, vcc
	v_cvt_f32_u32_e32 v89, v89
	v_cmp_gt_u32_e32 vcc, v93, v117
	v_subrev_u32_e32 v132, 32, v91
	v_mul_f32_e32 v89, v85, v89
	v_exp_f32_e32 v89, v89
	s_nop 0
	v_mul_f32_e32 v139, v89, v134
	v_subrev_u32_e32 v89, 19, v129
	v_cndmask_b32_e32 v89, v132, v89, vcc
	v_cvt_f32_u32_e32 v89, v89
	v_cmp_gt_u32_e32 vcc, v93, v118
	v_mul_f32_e32 v89, v85, v89
	v_exp_f32_e32 v89, v89
	s_nop 0
	v_mul_f32_e32 v140, v89, v135
	v_subrev_u32_e32 v89, 32, v129
	v_cndmask_b32_e32 v89, v141, v89, vcc
	v_cvt_f32_u32_e32 v89, v89
	v_mfma_f32_16x16x32_bf16 v[132:135], v[16:19], v[34:37], 0
	v_cmp_gt_u32_e32 vcc, v93, v119
	v_mul_f32_e32 v89, v85, v89
	v_mfma_f32_16x16x32_bf16 v[132:135], v[20:23], v[40:43], v[132:135]
	v_exp_f32_e32 v89, v89
	v_mfma_f32_16x16x32_bf16 v[34:37], v[24:27], v[34:37], 0
	v_mfma_f32_16x16x32_bf16 v[34:37], v[28:31], v[40:43], v[34:37]
	s_nop 4
	v_mul_f32_e32 v141, v89, v132
	v_subrev_u32_e32 v89, 33, v129
	v_subrev_u32_e32 v132, 18, v91
	v_cndmask_b32_e32 v89, v132, v89, vcc
	v_cvt_f32_u32_e32 v89, v89
	v_cmp_gt_u32_e32 vcc, v93, v120
	v_subrev_u32_e32 v132, 17, v91
	v_subrev_u32_e32 v40, 48, v129
	v_mul_f32_e32 v89, v85, v89
	v_exp_f32_e32 v89, v89
	v_add_u32_e32 v41, -3, v91
	v_mul_f32_e32 v142, v89, v133
	v_subrev_u32_e32 v89, 34, v129
	v_cndmask_b32_e32 v89, v132, v89, vcc
	v_cvt_f32_u32_e32 v89, v89
	v_cmp_gt_u32_e32 vcc, v93, v121
	v_subrev_u32_e32 v132, 35, v129
	v_cvt_pk_bf16_f32 v133, v139, v140
	v_mul_f32_e32 v89, v85, v89
	v_exp_f32_e32 v89, v89
	s_nop 0
	v_mul_f32_e32 v143, v89, v134
	v_add_u32_e32 v89, -16, v91
	v_cndmask_b32_e32 v132, v89, v132, vcc
	v_cmp_gt_u32_e32 vcc, v93, v122
	v_cvt_f32_u32_e32 v132, v132
	v_cvt_pk_bf16_f32 v134, v141, v142
	v_mul_f32_e32 v132, v85, v132
	v_cndmask_b32_e32 v40, v41, v40, vcc
	v_cvt_f32_u32_e32 v40, v40
	v_cmp_gt_u32_e32 vcc, v93, v123
	v_add_u32_e32 v41, -2, v91
	v_exp_f32_e32 v132, v132
	v_mul_f32_e32 v40, v85, v40
	v_exp_f32_e32 v40, v40
	v_mul_f32_e32 v135, v132, v135
	v_cvt_pk_bf16_f32 v132, v137, v138
	v_mul_f32_e32 v34, v40, v34
	v_subrev_u32_e32 v40, 49, v129
	v_cndmask_b32_e32 v40, v41, v40, vcc
	v_cvt_f32_u32_e32 v40, v40
	v_cmp_gt_u32_e32 vcc, v93, v124
	v_add_u32_e32 v41, -1, v91
	v_cvt_pk_bf16_f32 v135, v143, v135
	v_mul_f32_e32 v40, v85, v40
	v_exp_f32_e32 v40, v40
	s_nop 0
	v_mul_f32_e32 v35, v40, v35
	v_subrev_u32_e32 v40, 50, v129
	v_cndmask_b32_e32 v40, v41, v40, vcc
	v_cvt_f32_u32_e32 v40, v40
	v_cmp_gt_u32_e32 vcc, v93, v125
	v_cvt_pk_bf16_f32 v136, v34, v35
	v_mul_f32_e32 v40, v85, v40
	v_exp_f32_e32 v40, v40
	s_nop 0
	v_mul_f32_e32 v36, v40, v36
	v_subrev_u32_e32 v40, 51, v129
	v_cndmask_b32_e32 v40, v91, v40, vcc
	v_cvt_f32_u32_e32 v40, v40
	v_mul_f32_e32 v40, v85, v40
	v_exp_f32_e32 v40, v40
	s_nop 0
	v_mul_f32_e32 v37, v40, v37
	v_add_u32_e32 v40, v73, v62
	v_cvt_pk_bf16_f32 v137, v36, v37
	ds_read2_b64 v[34:37], v40 offset1:4
	ds_read2_b64 v[40:43], v40 offset0:8 offset1:12
	s_waitcnt lgkmcnt(1)
; __device__ __forceinline__ float sx(float v, int m, int lane) { return __builtin_bit_cast(float, __builtin_amdgcn_ds_bpermute((lane ^ m) << 2, __builtin_bit_cast(int, v))); }
; __device__ __forceinline__ void retout_item(const bf16_t* hbuf, const float* rot, const float* kvbuf, const float* normg, bf16_t* mixed, LAS bf16_t* vT, int item, int lane) {
;     ...
;         for (int et = 0; et < 4; ++et) { OT[et] = __builtin_amdgcn_mfma_f32_16x16x32_bf16(vt_frag(vT, et, 0, r, q), p0, OT[et], 0, 0, 0);
;             OT[et] = __builtin_amdgcn_mfma_f32_16x16x32_bf16(vt_frag(vT, et, 1, r, q), p1, OT[et], 0, 0, 0); }
;         float s = 0.f;
; #pragma unroll
;         for (int et = 0; et < 4; ++et) s += (OT[et][0] + OT[et][1]) + (OT[et][2] + OT[et][3]);
;         s += sx(s, 16, lane); s += sx(s, 32, lane);
;         const float mu = s * (1.0f / 64.0f); float v = 0.f;
; #pragma unroll
;         for (int et = 0; et < 4; ++et)
; #pragma unroll
;             for (int j = 0; j < 4; ++j) { const float d = OT[et][j] - mu; v += d * d; }
;         v += sx(v, 16, lane); v += sx(v, 32, lane);
;         const float rstd = rsqrtf(v * (1.0f / 64.0f) + LN_EPS);
; #pragma unroll
;         for (int et = 0; et < 4; ++et) { const int e = 16 * et + 4 * q;
;             const u32x2 gw = *(const u32x2*)(hbuf + (t0 + c) * INWP + C_RG + h * 64 + e); const f32x4 ng = *(const f32x4*)(normg + h * 64 + e);
	v_mfma_f32_16x16x32_bf16 v[34:37], v[34:37], v[130:133], v[56:59]
	s_nop 2
	v_add_u32_e32 v56, v105, v62
	s_waitcnt lgkmcnt(0)
	v_mfma_f32_16x16x32_bf16 v[40:43], v[40:43], v[134:137], v[34:37]
	s_nop 2
	ds_read2_b64 v[34:37], v56 offset1:4
	s_waitcnt lgkmcnt(0)
	v_mfma_f32_16x16x32_bf16 v[34:37], v[34:37], v[130:133], v[52:55]
	s_nop 2
	ds_read2_b64 v[52:55], v56 offset0:8 offset1:12
	v_add_u32_e32 v56, v107, v62
	s_waitcnt lgkmcnt(0)
	v_mfma_f32_16x16x32_bf16 v[34:37], v[52:55], v[134:137], v[34:37]
	ds_read2_b64 v[52:55], v56 offset1:4
	s_waitcnt lgkmcnt(0)
	v_mfma_f32_16x16x32_bf16 v[48:51], v[52:55], v[130:133], v[48:51]
	ds_read2_b64 v[52:55], v56 offset0:8 offset1:12
	s_waitcnt lgkmcnt(0)
	v_mfma_f32_16x16x32_bf16 v[50:53], v[52:55], v[134:137], v[48:51]
	s_nop 4
	v_add_u32_e32 v48, v109, v62
	ds_read2_b64 v[54:57], v48 offset1:4
	v_mov_b32_e32 v49, v37
	s_waitcnt lgkmcnt(0)
	v_mfma_f32_16x16x32_bf16 v[44:47], v[54:57], v[130:133], v[44:47]
	ds_read2_b64 v[54:57], v48 offset0:8 offset1:12
	v_mov_b32_e32 v48, v34
	s_waitcnt lgkmcnt(0)
	v_mfma_f32_16x16x32_bf16 v[130:133], v[54:57], v[134:137], v[44:47]
	s_nop 3
	v_mov_b32_e32 v44, v41
	v_mov_b32_e32 v45, v42
	v_mov_b32_e32 v46, v40
	v_mov_b32_e32 v47, v43
	v_pk_add_f32 v[44:45], v[44:45], v[46:47]
	v_mov_b32_e32 v46, v35
	v_mov_b32_e32 v47, v36
	v_pk_add_f32 v[46:47], v[46:47], v[48:49]
	v_add_f32_e32 v44, v44, v45
	v_pk_add_f32 v[46:47], v[46:47], v[46:47] op_sel:[0,1] op_sel_hi:[1,0]
	v_add_f32_e32 v44, 0, v44
	v_add_f32_e32 v48, v50, v51
	v_add_f32_e32 v54, v52, v53
	v_mov_b32_e32 v45, v130
	v_mov_b32_e32 v47, v131
	v_mov_b32_e32 v49, v132
	v_mov_b32_e32 v55, v133
	v_pk_add_f32 v[44:45], v[44:45], v[46:47]
	v_pk_add_f32 v[46:47], v[48:49], v[54:55]
	s_nop 0
	v_pk_add_f32 v[44:45], v[44:45], v[46:47]
	s_nop 0
	v_add_f32_e32 v44, v44, v45
	ds_bpermute_b32 v45, v69, v44
	s_waitcnt lgkmcnt(0)
	v_add_f32_e32 v44, v44, v45
	ds_bpermute_b32 v45, v71, v44
	s_waitcnt lgkmcnt(0)
	v_add_f32_e32 v45, v44, v45
	v_fmamk_f32 v59, v45, 0xbc800000, v41
	v_fmamk_f32 v55, v45, 0xbc800000, v40
	v_mul_f32_e32 v40, v59, v59
	v_fmac_f32_e32 v40, v55, v55
	v_fmamk_f32 v91, v45, 0xbc800000, v42
	v_fmac_f32_e32 v40, v91, v91
	v_fmac_f32_e32 v43, 0xbc800000, v45
	v_fmac_f32_e32 v40, v43, v43
	v_fmamk_f32 v58, v45, 0xbc800000, v34
	v_fmac_f32_e32 v40, v58, v58
	v_fmamk_f32 v57, v45, 0xbc800000, v35
	v_mul_f32_e32 v44, 0x3c800000, v45
	v_fmac_f32_e32 v40, v57, v57
	v_fmamk_f32 v36, v45, 0xbc800000, v36
	v_fmac_f32_e32 v40, v36, v36
	v_fmac_f32_e32 v37, 0xbc800000, v45
	v_pk_add_f32 v[50:51], v[50:51], v[44:45] op_sel_hi:[1,0] neg_lo:[0,1] neg_hi:[0,1]
	v_fmac_f32_e32 v40, v37, v37
	v_pk_mul_f32 v[34:35], v[50:51], v[50:51]
	v_pk_add_f32 v[48:49], v[52:53], v[44:45] op_sel_hi:[1,0] neg_lo:[0,1] neg_hi:[0,1]
	v_add_f32_e32 v34, v34, v40
	v_add_f32_e32 v40, v35, v34
	v_pk_mul_f32 v[34:35], v[48:49], v[48:49]
	v_pk_add_f32 v[46:47], v[130:131], v[44:45] op_sel_hi:[1,0] neg_lo:[0,1] neg_hi:[0,1]
	v_add_f32_e32 v34, v34, v40
	v_add_f32_e32 v40, v35, v34
	v_pk_mul_f32 v[34:35], v[46:47], v[46:47]
	v_pk_add_f32 v[44:45], v[132:133], v[44:45] op_sel_hi:[1,0] neg_lo:[0,1] neg_hi:[0,1]
	v_add_f32_e32 v34, v34, v40
	v_add_f32_e32 v40, v35, v34
	v_pk_mul_f32 v[34:35], v[44:45], v[44:45]
	v_lshl_add_u64 v[52:53], v[98:99], 0, s[36:37]
	global_load_dwordx2 v[144:145], v[52:53], off offset:-64
	global_load_dwordx4 v[152:155], v[96:97], off
	global_load_dwordx2 v[146:147], v[52:53], off offset:-32
	global_load_dwordx4 v[156:159], v[96:97], off offset:64
	global_load_dwordx2 v[148:149], v[52:53], off
	global_load_dwordx4 v[160:163], v[96:97], off offset:128
	global_load_dwordx2 v[150:151], v[52:53], off offset:32
	global_load_dwordx4 v[172:175], v[96:97], off offset:192
	v_add_f32_e32 v34, v34, v40
	v_add_f32_e32 v34, v35, v34
	ds_bpermute_b32 v35, v69, v34
	v_lshl_add_u64 v[98:99], v[98:99], 0, s[10:11]
	s_waitcnt lgkmcnt(0)
	v_add_f32_e32 v34, v34, v35
	ds_bpermute_b32 v35, v71, v34
	s_waitcnt lgkmcnt(0)
	v_add_f32_e32 v34, v34, v35
	v_fmamk_f32 v34, v34, 0x3c800000, v206
	v_cmp_gt_f32_e32 vcc, s33, v34
	v_mul_f32_e32 v35, 0x4b800000, v34
	s_nop 0
	v_cndmask_b32_e32 v34, v34, v35, vcc
	v_rsq_f32_e32 v34, v34
	s_nop 0
	v_mul_f32_e32 v35, 0x45800000, v34
	v_cndmask_b32_e32 v56, v34, v35, vcc
	v_mul_f32_e32 v41, v55, v56
	v_mul_f32_e32 v55, v91, v56
	v_mul_f32_e32 v43, v43, v56
	v_mov_b32_e32 v91, v89
	s_waitcnt vmcnt(0)
; __device__ __forceinline__ unsigned pk2(float lo, float hi) { unsigned r; asm("v_cvt_pk_bf16_f32 %0, %1, %2" : "=v"(r) : "v"(lo), "v"(hi)); return r; }
; __device__ __forceinline__ float bflo(unsigned u) { return __uint_as_float(u << 16); }
; __device__ __forceinline__ float bfhi(unsigned u) { return __uint_as_float(u & 0xffff0000u); }
; __device__ __forceinline__ float sl(float v, int src) { return __builtin_bit_cast(float, __builtin_amdgcn_ds_bpermute(src << 2, __builtin_bit_cast(int, v))); }
; __device__ __forceinline__ void retout_item(const bf16_t* hbuf, const float* rot, const float* kvbuf, const float* normg, bf16_t* mixed, LAS bf16_t* vT, int item, int lane) {
;     ...
;         for (int et = 0; et < 4; ++et) { const int e = 16 * et + 4 * q;
;             const u32x2 gw = *(const u32x2*)(hbuf + (t0 + c) * INWP + C_RG + h * 64 + e); const f32x4 ng = *(const f32x4*)(normg + h * 64 + e);
;             float gt[4] = {bflo(gw.x), bfhi(gw.x), bflo(gw.y), bfhi(gw.y)}, o[4];
; #pragma unroll
;             for (int j = 0; j < 4; ++j) { const float sl = gt[j] * __builtin_amdgcn_rcpf(1.0f + __expf(-gt[j])); o[j] = (OT[et][j] - mu) * rstd * ng[j] * sl; }
;             u32x2 w; w.x = pk2(o[0], o[1]); w.y = pk2(o[2], o[3]);
;             *(u32x2*)(mixed + (t0 + c) * 1024 + M_RET + h * 64 + e) = w; }
;     }
	v_mov_b32_e32 v34, v144
	v_mov_b32_e32 v35, v145
	v_lshlrev_b32_e32 v40, 16, v34
	v_lshlrev_b32_e32 v54, 16, v35
	v_and_b32_e32 v42, 0xffff0000, v35
	v_mul_f32_e32 v35, 0xbfb8aa3b, v40
	v_exp_f32_e32 v35, v35
	v_and_b32_e32 v34, 0xffff0000, v34
	v_mov_b32_e32 v130, v152
	v_mov_b32_e32 v131, v153
	v_mov_b32_e32 v132, v154
	v_mov_b32_e32 v133, v155
	v_mov_b32_e32 v135, v130
	v_add_f32_e32 v35, 1.0, v35
	v_rcp_f32_e32 v134, v35
	v_mul_f32_e32 v35, 0xbfb8aa3b, v34
	v_exp_f32_e32 v35, v35
	v_pk_mul_f32 v[40:41], v[134:135], v[40:41]
	s_nop 0
	v_mul_f32_e32 v40, v40, v41
	v_add_f32_e32 v35, 1.0, v35
	v_rcp_f32_e32 v130, v35
	v_mul_f32_e32 v35, v59, v56
	v_mul_f32_e32 v135, v36, v56
	v_pk_mul_f32 v[34:35], v[130:131], v[34:35]
	s_nop 0
	v_mul_f32_e32 v41, v34, v35
	v_mul_f32_e32 v34, 0xbfb8aa3b, v54
	v_exp_f32_e32 v34, v34
	v_mov_b32_e32 v35, v132
	v_mul_f32_e32 v131, v58, v56
	v_add_f32_e32 v34, 1.0, v34
	v_rcp_f32_e32 v34, v34
	s_nop 0
	v_pk_mul_f32 v[34:35], v[34:35], v[54:55]
	s_nop 0
	v_mul_f32_e32 v54, v34, v35
	v_mul_f32_e32 v34, 0xbfb8aa3b, v42
	v_exp_f32_e32 v34, v34
	s_nop 0
	v_add_f32_e32 v34, 1.0, v34
	v_rcp_f32_e32 v132, v34
	s_nop 0
	v_pk_mul_f32 v[34:35], v[132:133], v[42:43]
	s_nop 0
	v_mul_f32_e32 v35, v34, v35
	v_cvt_pk_bf16_f32 v35, v54, v35
	v_lshl_add_u64 v[54:55], v[102:103], 0, s[36:37]
	v_cvt_pk_bf16_f32 v34, v40, v41
	global_store_dwordx2 v[54:55], v[34:35], off offset:-64
	s_nop 0
	v_mul_f32_e32 v133, v57, v56
	v_lshl_add_u64 v[102:103], v[102:103], 0, s[20:21]
	v_mov_b32_e32 v34, v146
	v_mov_b32_e32 v35, v147
	v_lshlrev_b32_e32 v130, 16, v34
	v_and_b32_e32 v132, 0xffff0000, v34
	v_lshlrev_b32_e32 v134, 16, v35
	v_and_b32_e32 v34, 0xffff0000, v35
	v_mul_f32_e32 v35, 0xbfb8aa3b, v130
	v_exp_f32_e32 v35, v35
	v_mov_b32_e32 v40, v156
	v_mov_b32_e32 v41, v157
	v_mov_b32_e32 v42, v158
	v_mov_b32_e32 v43, v159
	v_mov_b32_e32 v137, v40
	v_add_f32_e32 v35, 1.0, v35
	v_rcp_f32_e32 v136, v35
	v_mul_f32_e32 v35, 0xbfb8aa3b, v132
	v_exp_f32_e32 v35, v35
	v_pk_mul_f32 v[58:59], v[136:137], v[130:131]
	s_nop 0
	v_mul_f32_e32 v58, v58, v59
	v_add_f32_e32 v35, 1.0, v35
	v_rcp_f32_e32 v40, v35
	v_mul_f32_e32 v35, 0xbfb8aa3b, v134
	v_exp_f32_e32 v35, v35
	v_mul_f32_e32 v59, v51, v56
	v_pk_mul_f32 v[40:41], v[40:41], v[132:133]
	v_mul_f32_e32 v131, v48, v56
	v_add_f32_e32 v35, 1.0, v35
	v_mul_f32_e32 v57, v40, v41
	v_rcp_f32_e32 v40, v35
	v_mul_f32_e32 v35, 0xbfb8aa3b, v34
	v_exp_f32_e32 v35, v35
	v_mov_b32_e32 v41, v42
	v_pk_mul_f32 v[40:41], v[40:41], v[134:135]
	v_mul_f32_e32 v51, v45, v56
	v_add_f32_e32 v35, 1.0, v35
	v_rcp_f32_e32 v42, v35
	v_mul_f32_e32 v35, v37, v56
	v_mul_f32_e32 v36, v40, v41
	v_pk_mul_f32 v[34:35], v[42:43], v[34:35]
	s_nop 0
	v_mul_f32_e32 v35, v34, v35
	v_cvt_pk_bf16_f32 v34, v58, v57
	v_cvt_pk_bf16_f32 v35, v36, v35
	global_store_dwordx2 v[54:55], v[34:35], off offset:-32
	s_nop 0
	v_mul_f32_e32 v43, v50, v56
	v_mov_b32_e32 v40, v148
	v_mov_b32_e32 v41, v149
	v_lshlrev_b32_e32 v42, 16, v40
	v_and_b32_e32 v58, 0xffff0000, v40
	v_lshlrev_b32_e32 v130, 16, v41
	v_and_b32_e32 v40, 0xffff0000, v41
	v_mul_f32_e32 v41, 0xbfb8aa3b, v42
	v_mov_b32_e32 v34, v160
	v_mov_b32_e32 v35, v161
	v_mov_b32_e32 v36, v162
	v_mov_b32_e32 v37, v163
	v_mov_b32_e32 v133, v34
	v_mul_f32_e32 v34, 0xbfb8aa3b, v58
	v_exp_f32_e32 v41, v41
	v_exp_f32_e32 v34, v34
	v_add_f32_e32 v41, 1.0, v41
	v_add_f32_e32 v34, 1.0, v34
	v_rcp_f32_e32 v132, v41
	v_rcp_f32_e32 v34, v34
	v_mul_f32_e32 v41, v49, v56
	v_mul_f32_e32 v49, v44, v56
	v_pk_mul_f32 v[42:43], v[132:133], v[42:43]
	v_pk_mul_f32 v[34:35], v[34:35], v[58:59]
	v_mul_f32_e32 v42, v42, v43
	v_mul_f32_e32 v43, v34, v35
	v_mul_f32_e32 v34, 0xbfb8aa3b, v130
	v_exp_f32_e32 v34, v34
	v_mov_b32_e32 v35, v36
	v_add_f32_e32 v34, 1.0, v34
	v_rcp_f32_e32 v34, v34
	s_nop 0
	v_pk_mul_f32 v[34:35], v[34:35], v[130:131]
	s_nop 0
	v_mul_f32_e32 v48, v34, v35
	v_mul_f32_e32 v34, 0xbfb8aa3b, v40
	v_exp_f32_e32 v34, v34
	s_nop 0
	v_add_f32_e32 v34, 1.0, v34
	v_rcp_f32_e32 v36, v34
	s_nop 0
	v_pk_mul_f32 v[34:35], v[36:37], v[40:41]
	s_nop 0
	v_mul_f32_e32 v35, v34, v35
	v_cvt_pk_bf16_f32 v34, v42, v43
	v_cvt_pk_bf16_f32 v35, v48, v35
	global_store_dwordx2 v[54:55], v[34:35], off
	s_nop 0
	v_mul_f32_e32 v43, v46, v56
	v_mov_b32_e32 v40, v150
	v_mov_b32_e32 v41, v151
	v_lshlrev_b32_e32 v42, 16, v40
	v_and_b32_e32 v40, 0xffff0000, v40
	v_mov_b32_e32 v34, v172
	v_mov_b32_e32 v35, v173
	v_mov_b32_e32 v36, v174
	v_mov_b32_e32 v37, v175
	v_mov_b32_e32 v53, v34
	v_mul_f32_e32 v34, 0xbfb8aa3b, v40
	v_exp_f32_e32 v34, v34
	v_lshlrev_b32_e32 v48, 16, v41
	v_and_b32_e32 v50, 0xffff0000, v41
	v_mul_f32_e32 v41, 0xbfb8aa3b, v42
	v_exp_f32_e32 v41, v41
	v_add_f32_e32 v34, 1.0, v34
	v_rcp_f32_e32 v34, v34
	v_add_f32_e32 v41, 1.0, v41
	v_rcp_f32_e32 v52, v41
	v_mul_f32_e32 v41, v47, v56
	v_pk_mul_f32 v[34:35], v[34:35], v[40:41]
	v_pk_mul_f32 v[42:43], v[52:53], v[42:43]
	v_mul_f32_e32 v40, v34, v35
	v_mul_f32_e32 v34, 0xbfb8aa3b, v48
	v_exp_f32_e32 v34, v34
	v_mov_b32_e32 v35, v36
	v_mul_f32_e32 v42, v42, v43
	v_add_f32_e32 v34, 1.0, v34
	v_rcp_f32_e32 v34, v34
	s_nop 0
	v_pk_mul_f32 v[34:35], v[34:35], v[48:49]
	s_nop 0
	v_mul_f32_e32 v41, v34, v35
	v_mul_f32_e32 v34, 0xbfb8aa3b, v50
	v_exp_f32_e32 v34, v34
	s_nop 0
	v_add_f32_e32 v34, 1.0, v34
	v_rcp_f32_e32 v36, v34
	s_nop 0
	v_pk_mul_f32 v[34:35], v[36:37], v[50:51]
	s_nop 0
	v_mul_f32_e32 v35, v34, v35
	v_cvt_pk_bf16_f32 v34, v42, v40
	v_cvt_pk_bf16_f32 v35, v41, v35
	global_store_dwordx2 v[54:55], v[34:35], off offset:32
	s_cbranch_scc1 .LBB0_176
	s_waitcnt lgkmcnt(0)
	s_add_i32 s0, s0, s14
	s_cmpk_gt_i32 s0, 0xbff
	s_cbranch_scc0 .LBB0_175

; #define LAS __attribute__((address_space(3)))
; __device__ __forceinline__ float bflo(unsigned u) { return __uint_as_float(u << 16); }
; __device__ __forceinline__ float bfhi(unsigned u) { return __uint_as_float(u & 0xffff0000u); }
; __device__ __forceinline__ float sx(float v, int m, int lane) { return __builtin_bit_cast(float, __builtin_amdgcn_ds_bpermute((lane ^ m) << 2, __builtin_bit_cast(int, v))); }
; __device__ __forceinline__ void sb_item(const bf16_t* hbuf, const float* kmax2, bf16_t* mixed, LAS bf16_t* vT, int item, int lane) {
;     const int bh = item >> 10, qt = item & 1023, b = bh / 6, h = bh % 6, tq0 = qt * 16; const size_t row0 = (size_t)b * SEQ + tq0;
;     const int r = lane & 15, q = lane >> 4;
;     bf16x8 qf[2]; float bound, carry = 0.f;
;     const float km2 = kmax2[bh];
;     { float s = 0.f;
; #pragma unroll
;       for (int ks = 0; ks < 2; ++ks) { const u32x4 v = *(const u32x4*)(hbuf + (row0 + r) * INWP + C_SBQ + h * 64 + 32 * ks + 8 * q); qf[ks] = as_bf16x8(v);
;           s += bflo(v.x) * bflo(v.x) + bfhi(v.x) * bfhi(v.x) + bflo(v.y) * bflo(v.y) + bfhi(v.y) * bfhi(v.y) + bflo(v.z) * bflo(v.z) + bfhi(v.z) * bfhi(v.z) + bflo(v.w) * bflo(v.w) + bfhi(v.w) * bfhi(v.w); }
;       s += sx(s, 16, lane); s += sx(s, 32, lane);
;       bound = sqrtf(s * km2) * 0.125f * 1.01f + 0.05f; }
;     const int qpos = tq0 + r;
;     f32x4 O[4];
; #pragma unroll
;     for (int et = 0; et < 4; ++et) O[et] = (f32x4){0.f, 0.f, 0.f, 0.f};
;     const int cr = lane >> 3, dc = lane & 7;
;     const bf16_t* seqp = hbuf + (size_t)b * SEQ * INWP + h * 64;
;     u32x4 vreg[8], kreg[8];
;     { const int k0 = tq0 + 16 - 64;
; #pragma unroll
;       for (int i = 0; i < 8; ++i) vreg[i] = *(const u32x4*)(seqp + (size_t)max(k0 + cr + 8 * i, 0) * INWP + C_SBV + 8 * dc);
; #pragma unroll
;       for (int i = 0; i < 8; ++i) kreg[i] = *(const u32x4*)(seqp + (size_t)max(k0 + 16 * (i >> 1) + r, 0) * INWP + C_SBK + 32 * (i & 1) + 8 * q); }
.LBB0_234:
	s_and_b32 s98, s12, 3
	s_lshl_b32 s98, s98, 3
	s_bfe_u32 s99, s12, 0x30002
	s_add_i32 s98, s98, s99
	s_and_b32 s99, s12, 0xffffffe0
	s_or_b32 s98, s98, s99
	s_ashr_i32 s0, s98, 10
	s_mul_hi_i32 s1, s0, 0x2aaaaaab
	s_lshr_b32 s17, s1, 31
	s_add_i32 s20, s1, s17
	s_mul_i32 s1, s20, 6
	s_sub_i32 s17, s0, s1
	s_lshl_b32 s1, s98, 4
	s_ashr_i32 s21, s20, 31
	s_and_b32 s26, s1, 0x3ff0
	s_lshl_b64 s[22:23], s[20:21], 14
	s_ashr_i32 s1, s0, 31
	s_or_b32 s21, s22, s26
	s_lshl_b64 s[0:1], s[0:1], 2
	s_add_u32 s0, s75, s0
	s_addc_u32 s1, s74, s1
	v_or_b32_e32 v34, s21, v122
	v_mov_b64_e32 v[8:9], s[42:43]
	s_lshl_b32 s72, s17, 6
	global_load_dword v16, v33, s[0:1] offset:1024
	v_mad_u64_u32 v[8:9], s[0:1], v34, s5, v[8:9]
	s_ashr_i32 s73, s72, 31
	v_mov_b32_e32 v35, s23
	v_mad_i32_i24 v9, s23, v207, v9
	s_lshl_b64 s[22:23], s[72:73], 1
	v_lshl_add_u64 v[8:9], v[8:9], 0, s[22:23]
	v_lshlrev_b32_e32 v32, 1, v124
	v_lshl_add_u64 v[12:13], v[8:9], 0, v[32:33]
	global_load_dwordx4 v[8:11], v[12:13], off offset:512
	s_mov_b32 s0, 0xf800000
	v_lshlrev_b32_e32 v88, 1, v126
	v_mov_b32_e32 v89, v33
	v_mov_b32_e32 v153, 0
	v_or_b32_e32 v155, s26, v122
	v_mov_b32_e32 v100, 0
	v_mov_b32_e32 v101, v153
	v_mov_b32_e32 v102, v153
	v_mov_b32_e32 v103, v153
	v_mov_b32_e32 v96, 0
	v_mov_b32_e32 v97, v153
	v_mov_b32_e32 v98, v153
	v_mov_b32_e32 v99, v153
	v_mov_b32_e32 v92, 0
	v_mov_b32_e32 v93, v153
	v_mov_b32_e32 v94, v153
	v_mov_b32_e32 v95, v153
	v_mov_b32_e32 v90, v153
	v_mov_b32_e32 v91, v153
	s_waitcnt vmcnt(0)
	v_and_b32_e32 v15, 0xffff0000, v8
	v_lshlrev_b32_e32 v14, 16, v8
	v_mul_f32_e32 v17, v15, v15
	v_fmac_f32_e32 v17, v14, v14
	v_lshlrev_b32_e32 v14, 16, v9
	v_fmac_f32_e32 v17, v14, v14
	v_and_b32_e32 v14, 0xffff0000, v9
	v_fmac_f32_e32 v17, v14, v14
	v_lshlrev_b32_e32 v14, 16, v10
	v_fmac_f32_e32 v17, v14, v14
	v_and_b32_e32 v14, 0xffff0000, v10
	v_fmac_f32_e32 v17, v14, v14
	v_lshlrev_b32_e32 v14, 16, v11
	v_fmac_f32_e32 v17, v14, v14
	v_and_b32_e32 v14, 0xffff0000, v11
	v_fmac_f32_e32 v17, v14, v14
	global_load_dwordx4 v[12:15], v[12:13], off offset:576
	s_waitcnt vmcnt(0)
	v_and_b32_e32 v19, 0xffff0000, v12
	v_lshlrev_b32_e32 v18, 16, v12
	v_mul_f32_e32 v19, v19, v19
	v_fmac_f32_e32 v19, v18, v18
	v_lshlrev_b32_e32 v18, 16, v13
	v_fmac_f32_e32 v19, v18, v18
	v_and_b32_e32 v18, 0xffff0000, v13
	v_fmac_f32_e32 v19, v18, v18
	v_lshlrev_b32_e32 v18, 16, v14
	v_fmac_f32_e32 v19, v18, v18
	v_and_b32_e32 v18, 0xffff0000, v14
	v_fmac_f32_e32 v19, v18, v18
	v_lshlrev_b32_e32 v18, 16, v15
	v_fmac_f32_e32 v19, v18, v18
	v_and_b32_e32 v18, 0xffff0000, v15
	v_fmac_f32_e32 v19, v18, v18
	v_add_f32_e32 v17, v17, v19
	ds_bpermute_b32 v18, v132, v17
	s_waitcnt lgkmcnt(0)
	v_add_f32_e32 v17, v17, v18
	ds_bpermute_b32 v18, v133, v17
	s_waitcnt lgkmcnt(0)
	v_add_f32_e32 v17, v17, v18
	v_mul_f32_e32 v16, v16, v17
	v_cmp_gt_f32_e32 vcc, s0, v16
	v_mul_f32_e32 v17, 0x4f800000, v16
	s_nop 0
	v_cndmask_b32_e32 v16, v16, v17, vcc
	v_sqrt_f32_e32 v17, v16
	s_nop 0
	v_add_u32_e32 v18, -1, v17
	v_fma_f32 v19, -v18, v17, v16
	v_cmp_ge_f32_e64 s[0:1], 0, v19
	v_add_u32_e32 v19, 1, v17
	s_nop 0
	v_cndmask_b32_e64 v18, v17, v18, s[0:1]
	v_fma_f32 v17, -v19, v17, v16
	v_cmp_lt_f32_e64 s[0:1], 0, v17
	s_nop 1
	v_cndmask_b32_e64 v17, v18, v19, s[0:1]
	s_mul_i32 s1, s20, 0x6000000
	s_mul_hi_i32 s0, s20, 0x6000000
	s_add_u32 s1, s42, s1
	v_mul_f32_e32 v18, 0x37800000, v17
	s_addc_u32 s17, s43, s0
	v_cndmask_b32_e32 v17, v17, v18, vcc
	v_cmp_class_f32_e32 vcc, v16, v209
	s_add_u32 s0, s1, s22
	s_addc_u32 s1, s17, s23
	v_cndmask_b32_e32 v16, v17, v16, vcc
	s_sub_i32 s17, s26, 48
	v_mul_f32_e32 v16, 0x3e000000, v16
	v_or_b32_e32 v48, s17, v122
	v_or_b32_e32 v86, s17, v134
	v_fmamk_f32 v154, v16, 0x3f8147ae, v170
	v_max_i32_e32 v16, 0xffffffd0, v48
	v_max_i32_e32 v24, 0xffffffe0, v48
	v_max_i32_e32 v40, -16, v48
	v_max_i32_e32 v64, 0xffffffd8, v86
	v_max_i32_e32 v68, 0xffffffe0, v86
	v_add_u32_e32 v16, 48, v16
	v_mov_b64_e32 v[84:85], s[0:1]
	v_add_u32_e32 v24, 32, v24
	v_add_u32_e32 v40, 16, v40
	v_max_i32_e32 v48, 0, v48
	v_add_u32_e32 v64, 40, v64
	v_add_u32_e32 v68, 32, v68
	v_mad_u64_u32 v[16:17], s[20:21], v16, s5, v[84:85]
	v_mad_u64_u32 v[24:25], s[20:21], v24, s5, v[84:85]
	v_mad_u64_u32 v[40:41], s[20:21], v40, s5, v[84:85]
	v_mad_u64_u32 v[48:49], s[20:21], v48, s5, v[84:85]
	v_mad_u64_u32 v[64:65], s[20:21], v64, s5, v[84:85]
	v_mad_u64_u32 v[68:69], s[20:21], v68, s5, v[84:85]
	v_lshl_add_u64 v[20:21], v[16:17], 0, v[32:33]
	v_lshl_add_u64 v[28:29], v[24:25], 0, v[32:33]
	v_lshl_add_u64 v[44:45], v[40:41], 0, v[32:33]
	v_lshl_add_u64 v[52:53], v[48:49], 0, v[32:33]
	v_lshl_add_u64 v[64:65], v[64:65], 0, v[88:89]
	v_lshl_add_u64 v[68:69], v[68:69], 0, v[88:89]
	global_load_dwordx4 v[16:19], v[20:21], off offset:1344
	s_nop 0
	global_load_dwordx4 v[20:23], v[20:21], off offset:1280
	s_nop 0
	global_load_dwordx4 v[24:27], v[28:29], off offset:1344
	s_nop 0
	global_load_dwordx4 v[28:31], v[28:29], off offset:1280
	s_nop 0
	global_load_dwordx4 v[40:43], v[44:45], off offset:1344
	s_nop 0
	global_load_dwordx4 v[44:47], v[44:45], off offset:1280
	s_nop 0
	global_load_dwordx4 v[48:51], v[52:53], off offset:1344
	s_nop 0
	global_load_dwordx4 v[52:55], v[52:53], off offset:1280
	v_max_i32_e32 v76, -16, v86
	global_load_dwordx4 v[64:67], v[64:65], off offset:2048
	v_add_u32_e32 v76, 16, v76
	global_load_dwordx4 v[72:75], v[68:69], off offset:2048
	v_max_i32_e32 v68, 0xffffffe8, v86
	v_add_u32_e32 v68, 24, v68
	v_mad_u64_u32 v[68:69], s[20:21], v68, s5, v[84:85]
	v_mad_u64_u32 v[76:77], s[20:21], v76, s5, v[84:85]
	v_lshl_add_u64 v[68:69], v[68:69], 0, v[88:89]
	v_lshl_add_u64 v[76:77], v[76:77], 0, v[88:89]
	v_max_i32_e32 v56, 0xffffffc8, v86
	v_max_i32_e32 v60, 0xffffffd0, v86
	global_load_dwordx4 v[68:71], v[68:69], off offset:2048
	v_add_u32_e32 v56, 56, v56
	global_load_dwordx4 v[80:83], v[76:77], off offset:2048
	v_or_b32_e32 v76, 8, v86
	v_add_u32_e32 v60, 48, v60
	v_max_i32_e32 v76, 0, v76
	v_max_i32_e32 v86, 0, v86
	v_mad_u64_u32 v[56:57], s[20:21], v56, s5, v[84:85]
	v_mad_u64_u32 v[60:61], s[20:21], v60, s5, v[84:85]
	v_mad_u64_u32 v[76:77], s[20:21], v76, s5, v[84:85]
	v_mad_u64_u32 v[84:85], s[20:21], v86, s5, v[84:85]
	v_lshl_add_u64 v[56:57], v[56:57], 0, v[88:89]
	v_lshl_add_u64 v[60:61], v[60:61], 0, v[88:89]
	v_lshl_add_u64 v[76:77], v[76:77], 0, v[88:89]
	v_lshl_add_u64 v[84:85], v[84:85], 0, v[88:89]
	global_load_dwordx4 v[56:59], v[56:57], off offset:2048
	v_lshl_add_u64 v[128:129], s[0:1], 0, v[88:89]
	global_load_dwordx4 v[60:63], v[60:61], off offset:2048
	v_lshl_add_u64 v[130:131], s[0:1], 0, v[32:33]
	global_load_dwordx4 v[76:79], v[76:77], off offset:2048
	v_mov_b32_e32 v88, 0
	global_load_dwordx4 v[84:87], v[84:85], off offset:2048
	v_mov_b32_e32 v89, v153
	s_branch .LBB0_236

; __device__ __forceinline__ float bflo(unsigned u) { return __uint_as_float(u << 16); }
; __device__ __forceinline__ float bfhi(unsigned u) { return __uint_as_float(u & 0xffff0000u); }
; __device__ __forceinline__ void pool_item(const bf16_t* hbuf, const bf16_t* pwT, const float* pscale, bf16_t* mixed, int item, int lane) {
;     const int k = item >> 11, gwi = item & 2047, g = (gwi + k) & 3, tile = (gwi >> 2) * 4 + k, t0 = tile * 16, w = 2 << g;
;     const int r = lane & 15, q = lane >> 4, t = t0 + r, ts = t % SEQ;
;     const bf16_t* up = hbuf + (size_t)t * INWP + g * 64 + 8 * q;
;     bf16x8 pf[2];
; #pragma unroll
;     for (int ks = 0; ks < 2; ++ks) { float s[8], u0[8];
; #pragma unroll
;         for (int e = 0; e < 8; ++e) s[e] = 0.f;
;         for (int i = 0; i < w; ++i) { if (ts - i >= 0) { const u32x4 v = *(const u32x4*)(up - (size_t)i * INWP + 32 * ks);
;             const float f[8] = {bflo(v.x), bfhi(v.x), bflo(v.y), bfhi(v.y), bflo(v.z), bfhi(v.z), bflo(v.w), bfhi(v.w)};
; #pragma unroll
;             for (int e = 0; e < 8; ++e) { s[e] += f[e]; if (i == 0) u0[e] = f[e]; } } }
.LBB0_329:
	s_or_b64 exec, exec, s[20:21]
	s_lshl_b32 s17, s15, 4
	s_and_b32 s20, s17, 0x7fc0
	s_lshl_b32 s21, s23, 4
	s_add_i32 s21, s21, s20
	v_or_b32_e32 v22, s21, v48
	v_mad_i64_i32 v[22:23], s[20:21], v22, s5, 0
	v_lshl_or_b32 v22, s22, 7, v22
	v_ashrrev_i32_e32 v9, 31, v8
	s_lshl_b32 s12, s22, 6
	s_lshl_b32 s17, 2, s22
	v_lshl_add_u64 v[28:29], v[18:19], 0, v[22:23]
	global_load_dwordx4 v[92:95], v[28:29], off
	v_lshl_add_u64 v[28:29], v[28:29], 0, s[2:3]
	s_cmp_eq_u32 s17, 2
	s_cbranch_scc1 .Lpl1_wait
	global_load_dwordx4 v[96:99], v[28:29], off
	v_lshl_add_u64 v[28:29], v[28:29], 0, s[2:3]
	global_load_dwordx4 v[100:103], v[28:29], off
	v_lshl_add_u64 v[28:29], v[28:29], 0, s[2:3]
	s_cmp_eq_u32 s17, 4
	s_cbranch_scc1 .Lpl1_wait
	global_load_dwordx4 v[104:107], v[28:29], off
	v_lshl_add_u64 v[28:29], v[28:29], 0, s[2:3]
	global_load_dwordx4 v[108:111], v[28:29], off
	v_lshl_add_u64 v[28:29], v[28:29], 0, s[2:3]
	global_load_dwordx4 v[112:115], v[28:29], off
	v_lshl_add_u64 v[28:29], v[28:29], 0, s[2:3]
	global_load_dwordx4 v[116:119], v[28:29], off
	v_lshl_add_u64 v[28:29], v[28:29], 0, s[2:3]
	s_cmp_eq_u32 s17, 8
	s_cbranch_scc1 .Lpl1_wait
	global_load_dwordx4 v[120:123], v[28:29], off
	v_lshl_add_u64 v[28:29], v[28:29], 0, s[2:3]
	global_load_dwordx4 v[124:127], v[28:29], off
	v_lshl_add_u64 v[28:29], v[28:29], 0, s[2:3]
	global_load_dwordx4 v[128:131], v[28:29], off
	v_lshl_add_u64 v[28:29], v[28:29], 0, s[2:3]
	global_load_dwordx4 v[132:135], v[28:29], off
	v_lshl_add_u64 v[28:29], v[28:29], 0, s[2:3]
	global_load_dwordx4 v[136:139], v[28:29], off
	v_lshl_add_u64 v[28:29], v[28:29], 0, s[2:3]
	global_load_dwordx4 v[140:143], v[28:29], off
	v_lshl_add_u64 v[28:29], v[28:29], 0, s[2:3]
	global_load_dwordx4 v[144:147], v[28:29], off
	v_lshl_add_u64 v[28:29], v[28:29], 0, s[2:3]
	global_load_dwordx4 v[148:151], v[28:29], off
	v_lshl_add_u64 v[28:29], v[28:29], 0, s[2:3]
.Lpl1_wait:
	s_waitcnt vmcnt(0)
	v_cmp_le_i32_e32 vcc, 1, v35
	s_and_saveexec_b64 s[20:21], vcc
	v_lshlrev_b32_e32 v30, 16, v92
	v_and_b32_e32 v31, 0xffff0000, v92
	v_pk_add_f32 v[26:27], v[26:27], v[30:31]
	v_lshlrev_b32_e32 v30, 16, v93
	v_and_b32_e32 v31, 0xffff0000, v93
	v_pk_add_f32 v[24:25], v[24:25], v[30:31]
	v_lshlrev_b32_e32 v30, 16, v94
	v_and_b32_e32 v31, 0xffff0000, v94
	v_pk_add_f32 v[2:3], v[2:3], v[30:31]
	v_lshlrev_b32_e32 v30, 16, v95
	v_and_b32_e32 v31, 0xffff0000, v95
	v_pk_add_f32 v[0:1], v[0:1], v[30:31]
	s_mov_b64 exec, s[20:21]
	s_cmp_eq_u32 s17, 2
	s_cbranch_scc1 .Lpl1_done
	v_cmp_le_i32_e32 vcc, 2, v35
	s_and_saveexec_b64 s[20:21], vcc
	v_lshlrev_b32_e32 v30, 16, v96
	v_and_b32_e32 v31, 0xffff0000, v96
	v_pk_add_f32 v[26:27], v[26:27], v[30:31]
	v_lshlrev_b32_e32 v30, 16, v97
	v_and_b32_e32 v31, 0xffff0000, v97
	v_pk_add_f32 v[24:25], v[24:25], v[30:31]
	v_lshlrev_b32_e32 v30, 16, v98
	v_and_b32_e32 v31, 0xffff0000, v98
	v_pk_add_f32 v[2:3], v[2:3], v[30:31]
	v_lshlrev_b32_e32 v30, 16, v99
	v_and_b32_e32 v31, 0xffff0000, v99
	v_pk_add_f32 v[0:1], v[0:1], v[30:31]
	s_mov_b64 exec, s[20:21]
	v_cmp_le_i32_e32 vcc, 3, v35
	s_and_saveexec_b64 s[20:21], vcc
	v_lshlrev_b32_e32 v30, 16, v100
	v_and_b32_e32 v31, 0xffff0000, v100
	v_pk_add_f32 v[26:27], v[26:27], v[30:31]
	v_lshlrev_b32_e32 v30, 16, v101
	v_and_b32_e32 v31, 0xffff0000, v101
	v_pk_add_f32 v[24:25], v[24:25], v[30:31]
	v_lshlrev_b32_e32 v30, 16, v102
	v_and_b32_e32 v31, 0xffff0000, v102
	v_pk_add_f32 v[2:3], v[2:3], v[30:31]
	v_lshlrev_b32_e32 v30, 16, v103
	v_and_b32_e32 v31, 0xffff0000, v103
	v_pk_add_f32 v[0:1], v[0:1], v[30:31]
	s_mov_b64 exec, s[20:21]
	s_cmp_eq_u32 s17, 4
	s_cbranch_scc1 .Lpl1_done
	v_cmp_le_i32_e32 vcc, 4, v35
	s_and_saveexec_b64 s[20:21], vcc
	v_lshlrev_b32_e32 v30, 16, v104
	v_and_b32_e32 v31, 0xffff0000, v104
	v_pk_add_f32 v[26:27], v[26:27], v[30:31]
	v_lshlrev_b32_e32 v30, 16, v105
	v_and_b32_e32 v31, 0xffff0000, v105
	v_pk_add_f32 v[24:25], v[24:25], v[30:31]
	v_lshlrev_b32_e32 v30, 16, v106
	v_and_b32_e32 v31, 0xffff0000, v106
	v_pk_add_f32 v[2:3], v[2:3], v[30:31]
	v_lshlrev_b32_e32 v30, 16, v107
	v_and_b32_e32 v31, 0xffff0000, v107
	v_pk_add_f32 v[0:1], v[0:1], v[30:31]
	s_mov_b64 exec, s[20:21]
	v_cmp_le_i32_e32 vcc, 5, v35
	s_and_saveexec_b64 s[20:21], vcc
	v_lshlrev_b32_e32 v30, 16, v108
	v_and_b32_e32 v31, 0xffff0000, v108
	v_pk_add_f32 v[26:27], v[26:27], v[30:31]
	v_lshlrev_b32_e32 v30, 16, v109
	v_and_b32_e32 v31, 0xffff0000, v109
	v_pk_add_f32 v[24:25], v[24:25], v[30:31]
	v_lshlrev_b32_e32 v30, 16, v110
	v_and_b32_e32 v31, 0xffff0000, v110
	v_pk_add_f32 v[2:3], v[2:3], v[30:31]
	v_lshlrev_b32_e32 v30, 16, v111
	v_and_b32_e32 v31, 0xffff0000, v111
	v_pk_add_f32 v[0:1], v[0:1], v[30:31]
	s_mov_b64 exec, s[20:21]
	v_cmp_le_i32_e32 vcc, 6, v35
	s_and_saveexec_b64 s[20:21], vcc
	v_lshlrev_b32_e32 v30, 16, v112
	v_and_b32_e32 v31, 0xffff0000, v112
	v_pk_add_f32 v[26:27], v[26:27], v[30:31]
	v_lshlrev_b32_e32 v30, 16, v113
	v_and_b32_e32 v31, 0xffff0000, v113
	v_pk_add_f32 v[24:25], v[24:25], v[30:31]
	v_lshlrev_b32_e32 v30, 16, v114
	v_and_b32_e32 v31, 0xffff0000, v114
	v_pk_add_f32 v[2:3], v[2:3], v[30:31]
	v_lshlrev_b32_e32 v30, 16, v115
	v_and_b32_e32 v31, 0xffff0000, v115
	v_pk_add_f32 v[0:1], v[0:1], v[30:31]
	s_mov_b64 exec, s[20:21]
	v_cmp_le_i32_e32 vcc, 7, v35
	s_and_saveexec_b64 s[20:21], vcc
	v_lshlrev_b32_e32 v30, 16, v116
	v_and_b32_e32 v31, 0xffff0000, v116
	v_pk_add_f32 v[26:27], v[26:27], v[30:31]
	v_lshlrev_b32_e32 v30, 16, v117
	v_and_b32_e32 v31, 0xffff0000, v117
	v_pk_add_f32 v[24:25], v[24:25], v[30:31]
	v_lshlrev_b32_e32 v30, 16, v118
	v_and_b32_e32 v31, 0xffff0000, v118
	v_pk_add_f32 v[2:3], v[2:3], v[30:31]
	v_lshlrev_b32_e32 v30, 16, v119
	v_and_b32_e32 v31, 0xffff0000, v119
	v_pk_add_f32 v[0:1], v[0:1], v[30:31]
	s_mov_b64 exec, s[20:21]
	s_cmp_eq_u32 s17, 8
	s_cbranch_scc1 .Lpl1_done
; __device__ __forceinline__ float bflo(unsigned u) { return __uint_as_float(u << 16); }
; __device__ __forceinline__ float bfhi(unsigned u) { return __uint_as_float(u & 0xffff0000u); }
; __device__ __forceinline__ void pool_item(const bf16_t* hbuf, const bf16_t* pwT, const float* pscale, bf16_t* mixed, int item, int lane) {
;     ...
;     for (int ks = 0; ks < 2; ++ks) { float s[8], u0[8];
; #pragma unroll
;         for (int e = 0; e < 8; ++e) s[e] = 0.f;
;         for (int i = 0; i < w; ++i) { if (ts - i >= 0) { const u32x4 v = *(const u32x4*)(up - (size_t)i * INWP + 32 * ks);
;             const float f[8] = {bflo(v.x), bfhi(v.x), bflo(v.y), bfhi(v.y), bflo(v.z), bfhi(v.z), bflo(v.w), bfhi(v.w)};
; #pragma unroll
;             for (int e = 0; e < 8; ++e) { s[e] += f[e]; if (i == 0) u0[e] = f[e]; } } }
;         const float cnt = (float)min(ts + 1, w); float o[8];
	v_cmp_le_i32_e32 vcc, 8, v35
	s_and_saveexec_b64 s[20:21], vcc
	v_lshlrev_b32_e32 v30, 16, v120
	v_and_b32_e32 v31, 0xffff0000, v120
	v_pk_add_f32 v[26:27], v[26:27], v[30:31]
	v_lshlrev_b32_e32 v30, 16, v121
	v_and_b32_e32 v31, 0xffff0000, v121
	v_pk_add_f32 v[24:25], v[24:25], v[30:31]
	v_lshlrev_b32_e32 v30, 16, v122
	v_and_b32_e32 v31, 0xffff0000, v122
	v_pk_add_f32 v[2:3], v[2:3], v[30:31]
	v_lshlrev_b32_e32 v30, 16, v123
	v_and_b32_e32 v31, 0xffff0000, v123
	v_pk_add_f32 v[0:1], v[0:1], v[30:31]
	s_mov_b64 exec, s[20:21]
	v_cmp_le_i32_e32 vcc, 9, v35
	s_and_saveexec_b64 s[20:21], vcc
	v_lshlrev_b32_e32 v30, 16, v124
	v_and_b32_e32 v31, 0xffff0000, v124
	v_pk_add_f32 v[26:27], v[26:27], v[30:31]
	v_lshlrev_b32_e32 v30, 16, v125
	v_and_b32_e32 v31, 0xffff0000, v125
	v_pk_add_f32 v[24:25], v[24:25], v[30:31]
	v_lshlrev_b32_e32 v30, 16, v126
	v_and_b32_e32 v31, 0xffff0000, v126
	v_pk_add_f32 v[2:3], v[2:3], v[30:31]
	v_lshlrev_b32_e32 v30, 16, v127
	v_and_b32_e32 v31, 0xffff0000, v127
	v_pk_add_f32 v[0:1], v[0:1], v[30:31]
	s_mov_b64 exec, s[20:21]
	v_cmp_le_i32_e32 vcc, 10, v35
	s_and_saveexec_b64 s[20:21], vcc
	v_lshlrev_b32_e32 v30, 16, v128
	v_and_b32_e32 v31, 0xffff0000, v128
	v_pk_add_f32 v[26:27], v[26:27], v[30:31]
	v_lshlrev_b32_e32 v30, 16, v129
	v_and_b32_e32 v31, 0xffff0000, v129
	v_pk_add_f32 v[24:25], v[24:25], v[30:31]
	v_lshlrev_b32_e32 v30, 16, v130
	v_and_b32_e32 v31, 0xffff0000, v130
	v_pk_add_f32 v[2:3], v[2:3], v[30:31]
	v_lshlrev_b32_e32 v30, 16, v131
	v_and_b32_e32 v31, 0xffff0000, v131
	v_pk_add_f32 v[0:1], v[0:1], v[30:31]
	s_mov_b64 exec, s[20:21]
	v_cmp_le_i32_e32 vcc, 11, v35
	s_and_saveexec_b64 s[20:21], vcc
	v_lshlrev_b32_e32 v30, 16, v132
	v_and_b32_e32 v31, 0xffff0000, v132
	v_pk_add_f32 v[26:27], v[26:27], v[30:31]
	v_lshlrev_b32_e32 v30, 16, v133
	v_and_b32_e32 v31, 0xffff0000, v133
	v_pk_add_f32 v[24:25], v[24:25], v[30:31]
	v_lshlrev_b32_e32 v30, 16, v134
	v_and_b32_e32 v31, 0xffff0000, v134
	v_pk_add_f32 v[2:3], v[2:3], v[30:31]
	v_lshlrev_b32_e32 v30, 16, v135
	v_and_b32_e32 v31, 0xffff0000, v135
	v_pk_add_f32 v[0:1], v[0:1], v[30:31]
	s_mov_b64 exec, s[20:21]
	v_cmp_le_i32_e32 vcc, 12, v35
	s_and_saveexec_b64 s[20:21], vcc
	v_lshlrev_b32_e32 v30, 16, v136
	v_and_b32_e32 v31, 0xffff0000, v136
	v_pk_add_f32 v[26:27], v[26:27], v[30:31]
	v_lshlrev_b32_e32 v30, 16, v137
	v_and_b32_e32 v31, 0xffff0000, v137
	v_pk_add_f32 v[24:25], v[24:25], v[30:31]
	v_lshlrev_b32_e32 v30, 16, v138
	v_and_b32_e32 v31, 0xffff0000, v138
	v_pk_add_f32 v[2:3], v[2:3], v[30:31]
	v_lshlrev_b32_e32 v30, 16, v139
	v_and_b32_e32 v31, 0xffff0000, v139
	v_pk_add_f32 v[0:1], v[0:1], v[30:31]
	s_mov_b64 exec, s[20:21]
	v_cmp_le_i32_e32 vcc, 13, v35
	s_and_saveexec_b64 s[20:21], vcc
	v_lshlrev_b32_e32 v30, 16, v140
	v_and_b32_e32 v31, 0xffff0000, v140
	v_pk_add_f32 v[26:27], v[26:27], v[30:31]
	v_lshlrev_b32_e32 v30, 16, v141
	v_and_b32_e32 v31, 0xffff0000, v141
	v_pk_add_f32 v[24:25], v[24:25], v[30:31]
	v_lshlrev_b32_e32 v30, 16, v142
	v_and_b32_e32 v31, 0xffff0000, v142
	v_pk_add_f32 v[2:3], v[2:3], v[30:31]
	v_lshlrev_b32_e32 v30, 16, v143
	v_and_b32_e32 v31, 0xffff0000, v143
	v_pk_add_f32 v[0:1], v[0:1], v[30:31]
	s_mov_b64 exec, s[20:21]
	v_cmp_le_i32_e32 vcc, 14, v35
	s_and_saveexec_b64 s[20:21], vcc
	v_lshlrev_b32_e32 v30, 16, v144
	v_and_b32_e32 v31, 0xffff0000, v144
	v_pk_add_f32 v[26:27], v[26:27], v[30:31]
	v_lshlrev_b32_e32 v30, 16, v145
	v_and_b32_e32 v31, 0xffff0000, v145
	v_pk_add_f32 v[24:25], v[24:25], v[30:31]
	v_lshlrev_b32_e32 v30, 16, v146
	v_and_b32_e32 v31, 0xffff0000, v146
	v_pk_add_f32 v[2:3], v[2:3], v[30:31]
	v_lshlrev_b32_e32 v30, 16, v147
	v_and_b32_e32 v31, 0xffff0000, v147
	v_pk_add_f32 v[0:1], v[0:1], v[30:31]
	s_mov_b64 exec, s[20:21]
	v_cmp_le_i32_e32 vcc, 15, v35
	s_and_saveexec_b64 s[20:21], vcc
	v_lshlrev_b32_e32 v30, 16, v148
	v_and_b32_e32 v31, 0xffff0000, v148
	v_pk_add_f32 v[26:27], v[26:27], v[30:31]
	v_lshlrev_b32_e32 v30, 16, v149
	v_and_b32_e32 v31, 0xffff0000, v149
	v_pk_add_f32 v[24:25], v[24:25], v[30:31]
	v_lshlrev_b32_e32 v30, 16, v150
	v_and_b32_e32 v31, 0xffff0000, v150
	v_pk_add_f32 v[2:3], v[2:3], v[30:31]
	v_lshlrev_b32_e32 v30, 16, v151
	v_and_b32_e32 v31, 0xffff0000, v151
	v_pk_add_f32 v[0:1], v[0:1], v[30:31]
	s_mov_b64 exec, s[20:21]
.Lpl1_done:
	s_mov_b32 s22, s17

; __device__ __forceinline__ float bflo(unsigned u) { return __uint_as_float(u << 16); }
; __device__ __forceinline__ float bfhi(unsigned u) { return __uint_as_float(u & 0xffff0000u); }
; __device__ __forceinline__ void pool_item(const bf16_t* hbuf, const bf16_t* pwT, const float* pscale, bf16_t* mixed, int item, int lane) {
;     ...
;     for (int ks = 0; ks < 2; ++ks) { float s[8], u0[8];
; #pragma unroll
;         for (int e = 0; e < 8; ++e) s[e] = 0.f;
;         for (int i = 0; i < w; ++i) { if (ts - i >= 0) { const u32x4 v = *(const u32x4*)(up - (size_t)i * INWP + 32 * ks);
;             const float f[8] = {bflo(v.x), bfhi(v.x), bflo(v.y), bfhi(v.y), bflo(v.z), bfhi(v.z), bflo(v.w), bfhi(v.w)};
; #pragma unroll
;             for (int e = 0; e < 8; ++e) { s[e] += f[e]; if (i == 0) u0[e] = f[e]; } } }
;         const float cnt = (float)min(ts + 1, w); float o[8];
.LBB0_335:
	s_or_b64 exec, exec, s[20:21]
	v_lshl_add_u64 v[14:15], v[20:21], 0, v[22:23]
	global_load_dwordx4 v[92:95], v[14:15], off
	v_lshl_add_u64 v[14:15], v[14:15], 0, s[2:3]
	s_cmp_eq_u32 s17, 2
	s_cbranch_scc1 .Lpl2_wait
	global_load_dwordx4 v[96:99], v[14:15], off
	v_lshl_add_u64 v[14:15], v[14:15], 0, s[2:3]
	global_load_dwordx4 v[100:103], v[14:15], off
	v_lshl_add_u64 v[14:15], v[14:15], 0, s[2:3]
	s_cmp_eq_u32 s17, 4
	s_cbranch_scc1 .Lpl2_wait
	global_load_dwordx4 v[104:107], v[14:15], off
	v_lshl_add_u64 v[14:15], v[14:15], 0, s[2:3]
	global_load_dwordx4 v[108:111], v[14:15], off
	v_lshl_add_u64 v[14:15], v[14:15], 0, s[2:3]
	global_load_dwordx4 v[112:115], v[14:15], off
	v_lshl_add_u64 v[14:15], v[14:15], 0, s[2:3]
	global_load_dwordx4 v[116:119], v[14:15], off
	v_lshl_add_u64 v[14:15], v[14:15], 0, s[2:3]
	s_cmp_eq_u32 s17, 8
	s_cbranch_scc1 .Lpl2_wait
	global_load_dwordx4 v[120:123], v[14:15], off
	v_lshl_add_u64 v[14:15], v[14:15], 0, s[2:3]
	global_load_dwordx4 v[124:127], v[14:15], off
	v_lshl_add_u64 v[14:15], v[14:15], 0, s[2:3]
	global_load_dwordx4 v[128:131], v[14:15], off
	v_lshl_add_u64 v[14:15], v[14:15], 0, s[2:3]
	global_load_dwordx4 v[132:135], v[14:15], off
	v_lshl_add_u64 v[14:15], v[14:15], 0, s[2:3]
	global_load_dwordx4 v[136:139], v[14:15], off
	v_lshl_add_u64 v[14:15], v[14:15], 0, s[2:3]
	global_load_dwordx4 v[140:143], v[14:15], off
	v_lshl_add_u64 v[14:15], v[14:15], 0, s[2:3]
	global_load_dwordx4 v[144:147], v[14:15], off
	v_lshl_add_u64 v[14:15], v[14:15], 0, s[2:3]
	global_load_dwordx4 v[148:151], v[14:15], off
	v_lshl_add_u64 v[14:15], v[14:15], 0, s[2:3]
.Lpl2_wait:
	s_waitcnt vmcnt(0)
	v_cmp_le_i32_e32 vcc, 1, v35
	s_and_saveexec_b64 s[0:1], vcc
	v_lshlrev_b32_e32 v22, 16, v92
	v_and_b32_e32 v23, 0xffff0000, v92
	v_pk_add_f32 v[30:31], v[30:31], v[22:23]
	v_lshlrev_b32_e32 v22, 16, v93
	v_and_b32_e32 v23, 0xffff0000, v93
	v_pk_add_f32 v[28:29], v[28:29], v[22:23]
	v_lshlrev_b32_e32 v22, 16, v94
	v_and_b32_e32 v23, 0xffff0000, v94
	v_pk_add_f32 v[26:27], v[26:27], v[22:23]
	v_lshlrev_b32_e32 v22, 16, v95
	v_and_b32_e32 v23, 0xffff0000, v95
	v_pk_add_f32 v[24:25], v[24:25], v[22:23]
	s_mov_b64 exec, s[0:1]
	s_cmp_eq_u32 s17, 2
	s_cbranch_scc1 .Lpl2_done
	v_cmp_le_i32_e32 vcc, 2, v35
	s_and_saveexec_b64 s[0:1], vcc
	v_lshlrev_b32_e32 v22, 16, v96
	v_and_b32_e32 v23, 0xffff0000, v96
	v_pk_add_f32 v[30:31], v[30:31], v[22:23]
	v_lshlrev_b32_e32 v22, 16, v97
	v_and_b32_e32 v23, 0xffff0000, v97
	v_pk_add_f32 v[28:29], v[28:29], v[22:23]
	v_lshlrev_b32_e32 v22, 16, v98
	v_and_b32_e32 v23, 0xffff0000, v98
	v_pk_add_f32 v[26:27], v[26:27], v[22:23]
	v_lshlrev_b32_e32 v22, 16, v99
	v_and_b32_e32 v23, 0xffff0000, v99
	v_pk_add_f32 v[24:25], v[24:25], v[22:23]
	s_mov_b64 exec, s[0:1]
	v_cmp_le_i32_e32 vcc, 3, v35
	s_and_saveexec_b64 s[0:1], vcc
	v_lshlrev_b32_e32 v22, 16, v100
	v_and_b32_e32 v23, 0xffff0000, v100
	v_pk_add_f32 v[30:31], v[30:31], v[22:23]
	v_lshlrev_b32_e32 v22, 16, v101
	v_and_b32_e32 v23, 0xffff0000, v101
	v_pk_add_f32 v[28:29], v[28:29], v[22:23]
	v_lshlrev_b32_e32 v22, 16, v102
	v_and_b32_e32 v23, 0xffff0000, v102
	v_pk_add_f32 v[26:27], v[26:27], v[22:23]
	v_lshlrev_b32_e32 v22, 16, v103
	v_and_b32_e32 v23, 0xffff0000, v103
	v_pk_add_f32 v[24:25], v[24:25], v[22:23]
	s_mov_b64 exec, s[0:1]
	s_cmp_eq_u32 s17, 4
	s_cbranch_scc1 .Lpl2_done
	v_cmp_le_i32_e32 vcc, 4, v35
	s_and_saveexec_b64 s[0:1], vcc
	v_lshlrev_b32_e32 v22, 16, v104
	v_and_b32_e32 v23, 0xffff0000, v104
	v_pk_add_f32 v[30:31], v[30:31], v[22:23]
	v_lshlrev_b32_e32 v22, 16, v105
	v_and_b32_e32 v23, 0xffff0000, v105
	v_pk_add_f32 v[28:29], v[28:29], v[22:23]
	v_lshlrev_b32_e32 v22, 16, v106
	v_and_b32_e32 v23, 0xffff0000, v106
	v_pk_add_f32 v[26:27], v[26:27], v[22:23]
	v_lshlrev_b32_e32 v22, 16, v107
	v_and_b32_e32 v23, 0xffff0000, v107
	v_pk_add_f32 v[24:25], v[24:25], v[22:23]
	s_mov_b64 exec, s[0:1]
	v_cmp_le_i32_e32 vcc, 5, v35
	s_and_saveexec_b64 s[0:1], vcc
	v_lshlrev_b32_e32 v22, 16, v108
	v_and_b32_e32 v23, 0xffff0000, v108
	v_pk_add_f32 v[30:31], v[30:31], v[22:23]
	v_lshlrev_b32_e32 v22, 16, v109
	v_and_b32_e32 v23, 0xffff0000, v109
	v_pk_add_f32 v[28:29], v[28:29], v[22:23]
	v_lshlrev_b32_e32 v22, 16, v110
	v_and_b32_e32 v23, 0xffff0000, v110
	v_pk_add_f32 v[26:27], v[26:27], v[22:23]
	v_lshlrev_b32_e32 v22, 16, v111
	v_and_b32_e32 v23, 0xffff0000, v111
	v_pk_add_f32 v[24:25], v[24:25], v[22:23]
	s_mov_b64 exec, s[0:1]
	v_cmp_le_i32_e32 vcc, 6, v35
	s_and_saveexec_b64 s[0:1], vcc
	v_lshlrev_b32_e32 v22, 16, v112
	v_and_b32_e32 v23, 0xffff0000, v112
	v_pk_add_f32 v[30:31], v[30:31], v[22:23]
	v_lshlrev_b32_e32 v22, 16, v113
	v_and_b32_e32 v23, 0xffff0000, v113
	v_pk_add_f32 v[28:29], v[28:29], v[22:23]
	v_lshlrev_b32_e32 v22, 16, v114
	v_and_b32_e32 v23, 0xffff0000, v114
	v_pk_add_f32 v[26:27], v[26:27], v[22:23]
	v_lshlrev_b32_e32 v22, 16, v115
	v_and_b32_e32 v23, 0xffff0000, v115
	v_pk_add_f32 v[24:25], v[24:25], v[22:23]
	s_mov_b64 exec, s[0:1]
	v_cmp_le_i32_e32 vcc, 7, v35
	s_and_saveexec_b64 s[0:1], vcc
	v_lshlrev_b32_e32 v22, 16, v116
	v_and_b32_e32 v23, 0xffff0000, v116
	v_pk_add_f32 v[30:31], v[30:31], v[22:23]
	v_lshlrev_b32_e32 v22, 16, v117
	v_and_b32_e32 v23, 0xffff0000, v117
	v_pk_add_f32 v[28:29], v[28:29], v[22:23]
	v_lshlrev_b32_e32 v22, 16, v118
	v_and_b32_e32 v23, 0xffff0000, v118
	v_pk_add_f32 v[26:27], v[26:27], v[22:23]
	v_lshlrev_b32_e32 v22, 16, v119
	v_and_b32_e32 v23, 0xffff0000, v119
	v_pk_add_f32 v[24:25], v[24:25], v[22:23]
	s_mov_b64 exec, s[0:1]
	s_cmp_eq_u32 s17, 8
	s_cbranch_scc1 .Lpl2_done
; __device__ __forceinline__ float bflo(unsigned u) { return __uint_as_float(u << 16); }
; __device__ __forceinline__ float bfhi(unsigned u) { return __uint_as_float(u & 0xffff0000u); }
; __device__ __forceinline__ void pool_item(const bf16_t* hbuf, const bf16_t* pwT, const float* pscale, bf16_t* mixed, int item, int lane) {
;     ...
;     for (int ks = 0; ks < 2; ++ks) { float s[8], u0[8];
; #pragma unroll
;         for (int e = 0; e < 8; ++e) s[e] = 0.f;
;         for (int i = 0; i < w; ++i) { if (ts - i >= 0) { const u32x4 v = *(const u32x4*)(up - (size_t)i * INWP + 32 * ks);
;             const float f[8] = {bflo(v.x), bfhi(v.x), bflo(v.y), bfhi(v.y), bflo(v.z), bfhi(v.z), bflo(v.w), bfhi(v.w)};
; #pragma unroll
;             for (int e = 0; e < 8; ++e) { s[e] += f[e]; if (i == 0) u0[e] = f[e]; } } }
;         const float cnt = (float)min(ts + 1, w); float o[8];
	v_cmp_le_i32_e32 vcc, 8, v35
	s_and_saveexec_b64 s[0:1], vcc
	v_lshlrev_b32_e32 v22, 16, v120
	v_and_b32_e32 v23, 0xffff0000, v120
	v_pk_add_f32 v[30:31], v[30:31], v[22:23]
	v_lshlrev_b32_e32 v22, 16, v121
	v_and_b32_e32 v23, 0xffff0000, v121
	v_pk_add_f32 v[28:29], v[28:29], v[22:23]
	v_lshlrev_b32_e32 v22, 16, v122
	v_and_b32_e32 v23, 0xffff0000, v122
	v_pk_add_f32 v[26:27], v[26:27], v[22:23]
	v_lshlrev_b32_e32 v22, 16, v123
	v_and_b32_e32 v23, 0xffff0000, v123
	v_pk_add_f32 v[24:25], v[24:25], v[22:23]
	s_mov_b64 exec, s[0:1]
	v_cmp_le_i32_e32 vcc, 9, v35
	s_and_saveexec_b64 s[0:1], vcc
	v_lshlrev_b32_e32 v22, 16, v124
	v_and_b32_e32 v23, 0xffff0000, v124
	v_pk_add_f32 v[30:31], v[30:31], v[22:23]
	v_lshlrev_b32_e32 v22, 16, v125
	v_and_b32_e32 v23, 0xffff0000, v125
	v_pk_add_f32 v[28:29], v[28:29], v[22:23]
	v_lshlrev_b32_e32 v22, 16, v126
	v_and_b32_e32 v23, 0xffff0000, v126
	v_pk_add_f32 v[26:27], v[26:27], v[22:23]
	v_lshlrev_b32_e32 v22, 16, v127
	v_and_b32_e32 v23, 0xffff0000, v127
	v_pk_add_f32 v[24:25], v[24:25], v[22:23]
	s_mov_b64 exec, s[0:1]
	v_cmp_le_i32_e32 vcc, 10, v35
	s_and_saveexec_b64 s[0:1], vcc
	v_lshlrev_b32_e32 v22, 16, v128
	v_and_b32_e32 v23, 0xffff0000, v128
	v_pk_add_f32 v[30:31], v[30:31], v[22:23]
	v_lshlrev_b32_e32 v22, 16, v129
	v_and_b32_e32 v23, 0xffff0000, v129
	v_pk_add_f32 v[28:29], v[28:29], v[22:23]
	v_lshlrev_b32_e32 v22, 16, v130
	v_and_b32_e32 v23, 0xffff0000, v130
	v_pk_add_f32 v[26:27], v[26:27], v[22:23]
	v_lshlrev_b32_e32 v22, 16, v131
	v_and_b32_e32 v23, 0xffff0000, v131
	v_pk_add_f32 v[24:25], v[24:25], v[22:23]
	s_mov_b64 exec, s[0:1]
	v_cmp_le_i32_e32 vcc, 11, v35
	s_and_saveexec_b64 s[0:1], vcc
	v_lshlrev_b32_e32 v22, 16, v132
	v_and_b32_e32 v23, 0xffff0000, v132
	v_pk_add_f32 v[30:31], v[30:31], v[22:23]
	v_lshlrev_b32_e32 v22, 16, v133
	v_and_b32_e32 v23, 0xffff0000, v133
	v_pk_add_f32 v[28:29], v[28:29], v[22:23]
	v_lshlrev_b32_e32 v22, 16, v134
	v_and_b32_e32 v23, 0xffff0000, v134
	v_pk_add_f32 v[26:27], v[26:27], v[22:23]
	v_lshlrev_b32_e32 v22, 16, v135
	v_and_b32_e32 v23, 0xffff0000, v135
	v_pk_add_f32 v[24:25], v[24:25], v[22:23]
	s_mov_b64 exec, s[0:1]
	v_cmp_le_i32_e32 vcc, 12, v35
	s_and_saveexec_b64 s[0:1], vcc
	v_lshlrev_b32_e32 v22, 16, v136
	v_and_b32_e32 v23, 0xffff0000, v136
	v_pk_add_f32 v[30:31], v[30:31], v[22:23]
	v_lshlrev_b32_e32 v22, 16, v137
	v_and_b32_e32 v23, 0xffff0000, v137
	v_pk_add_f32 v[28:29], v[28:29], v[22:23]
	v_lshlrev_b32_e32 v22, 16, v138
	v_and_b32_e32 v23, 0xffff0000, v138
	v_pk_add_f32 v[26:27], v[26:27], v[22:23]
	v_lshlrev_b32_e32 v22, 16, v139
	v_and_b32_e32 v23, 0xffff0000, v139
	v_pk_add_f32 v[24:25], v[24:25], v[22:23]
	s_mov_b64 exec, s[0:1]
	v_cmp_le_i32_e32 vcc, 13, v35
	s_and_saveexec_b64 s[0:1], vcc
	v_lshlrev_b32_e32 v22, 16, v140
	v_and_b32_e32 v23, 0xffff0000, v140
	v_pk_add_f32 v[30:31], v[30:31], v[22:23]
	v_lshlrev_b32_e32 v22, 16, v141
	v_and_b32_e32 v23, 0xffff0000, v141
	v_pk_add_f32 v[28:29], v[28:29], v[22:23]
	v_lshlrev_b32_e32 v22, 16, v142
	v_and_b32_e32 v23, 0xffff0000, v142
	v_pk_add_f32 v[26:27], v[26:27], v[22:23]
	v_lshlrev_b32_e32 v22, 16, v143
	v_and_b32_e32 v23, 0xffff0000, v143
	v_pk_add_f32 v[24:25], v[24:25], v[22:23]
	s_mov_b64 exec, s[0:1]
	v_cmp_le_i32_e32 vcc, 14, v35
	s_and_saveexec_b64 s[0:1], vcc
	v_lshlrev_b32_e32 v22, 16, v144
	v_and_b32_e32 v23, 0xffff0000, v144
	v_pk_add_f32 v[30:31], v[30:31], v[22:23]
	v_lshlrev_b32_e32 v22, 16, v145
	v_and_b32_e32 v23, 0xffff0000, v145
	v_pk_add_f32 v[28:29], v[28:29], v[22:23]
	v_lshlrev_b32_e32 v22, 16, v146
	v_and_b32_e32 v23, 0xffff0000, v146
	v_pk_add_f32 v[26:27], v[26:27], v[22:23]
	v_lshlrev_b32_e32 v22, 16, v147
	v_and_b32_e32 v23, 0xffff0000, v147
	v_pk_add_f32 v[24:25], v[24:25], v[22:23]
	s_mov_b64 exec, s[0:1]
	v_cmp_le_i32_e32 vcc, 15, v35
	s_and_saveexec_b64 s[0:1], vcc
	v_lshlrev_b32_e32 v22, 16, v148
	v_and_b32_e32 v23, 0xffff0000, v148
	v_pk_add_f32 v[30:31], v[30:31], v[22:23]
	v_lshlrev_b32_e32 v22, 16, v149
	v_and_b32_e32 v23, 0xffff0000, v149
	v_pk_add_f32 v[28:29], v[28:29], v[22:23]
	v_lshlrev_b32_e32 v22, 16, v150
	v_and_b32_e32 v23, 0xffff0000, v150
	v_pk_add_f32 v[26:27], v[26:27], v[22:23]
	v_lshlrev_b32_e32 v22, 16, v151
	v_and_b32_e32 v23, 0xffff0000, v151
	v_pk_add_f32 v[24:25], v[24:25], v[22:23]
	s_mov_b64 exec, s[0:1]
.Lpl2_done:
	s_mov_b32 s20, s17
	s_branch .LBB0_326

; __global__ void __launch_bounds__(512, 2) mega(Args a) {
	.amdhsa_kernel _Z4mega4Args
		.amdhsa_group_segment_fixed_size 0
		.amdhsa_private_segment_fixed_size 0
		.amdhsa_kernarg_size 440
		.amdhsa_user_sgpr_count 2
		.amdhsa_user_sgpr_dispatch_ptr 0
		.amdhsa_user_sgpr_queue_ptr 0
		.amdhsa_user_sgpr_kernarg_segment_ptr 1
		.amdhsa_user_sgpr_dispatch_id 0
		.amdhsa_user_sgpr_kernarg_preload_length 0
		.amdhsa_user_sgpr_kernarg_preload_offset 0
		.amdhsa_user_sgpr_private_segment_size 0
		.amdhsa_uses_dynamic_stack 0
		.amdhsa_enable_private_segment 0
		.amdhsa_system_sgpr_workgroup_id_x 1
		.amdhsa_system_sgpr_workgroup_id_y 0
		.amdhsa_system_sgpr_workgroup_id_z 0
		.amdhsa_system_sgpr_workgroup_info 0
		.amdhsa_system_vgpr_workitem_id 2
		.amdhsa_next_free_vgpr 255
		.amdhsa_next_free_sgpr 102
		.amdhsa_accum_offset 256
		.amdhsa_reserve_vcc 1
		.amdhsa_float_round_mode_32 0
		.amdhsa_float_round_mode_16_64 0
		.amdhsa_float_denorm_mode_32 3
		.amdhsa_float_denorm_mode_16_64 3
		.amdhsa_dx10_clamp 1
		.amdhsa_ieee_mode 1
		.amdhsa_fp16_overflow 0
		.amdhsa_tg_split 0
		.amdhsa_exception_fp_ieee_invalid_op 0
		.amdhsa_exception_fp_denorm_src 0
		.amdhsa_exception_fp_ieee_div_zero 0
		.amdhsa_exception_fp_ieee_overflow 0
		.amdhsa_exception_fp_ieee_underflow 0
		.amdhsa_exception_fp_ieee_inexact 0
		.amdhsa_exception_int_div_zero 0
	.end_amdhsa_kernel

; __global__ void __launch_bounds__(512, 2) mega(Args a) {
amdhsa.kernels:
  - .agpr_count:     0
    .args:
      - .offset:         0
        .size:           184
        .value_kind:     by_value
      - .offset:         184
        .size:           4
        .value_kind:     hidden_block_count_x
      - .offset:         188
        .size:           4
        .value_kind:     hidden_block_count_y
      - .offset:         192
        .size:           4
        .value_kind:     hidden_block_count_z
      - .offset:         196
        .size:           2
        .value_kind:     hidden_group_size_x
      - .offset:         198
        .size:           2
        .value_kind:     hidden_group_size_y
      - .offset:         200
        .size:           2
        .value_kind:     hidden_group_size_z
      - .offset:         202
        .size:           2
        .value_kind:     hidden_remainder_x
      - .offset:         204
        .size:           2
        .value_kind:     hidden_remainder_y
      - .offset:         206
        .size:           2
        .value_kind:     hidden_remainder_z
      - .offset:         224
        .size:           8
        .value_kind:     hidden_global_offset_x
      - .offset:         232
        .size:           8
        .value_kind:     hidden_global_offset_y
      - .offset:         240
        .size:           8
        .value_kind:     hidden_global_offset_z
      - .offset:         248
        .size:           2
        .value_kind:     hidden_grid_dims
      - .offset:         272
        .size:           8
        .value_kind:     hidden_multigrid_sync_arg
      - .offset:         304
        .size:           4
        .value_kind:     hidden_dynamic_lds_size
    .group_segment_fixed_size: 0
    .kernarg_segment_align: 8
    .kernarg_segment_size: 440
    .language:       OpenCL C
    .language_version:
      - 2
      - 0
    .max_flat_workgroup_size: 512
    .name:           _Z4mega4Args
    .private_segment_fixed_size: 0
    .sgpr_count:     108
    .sgpr_spill_count: 331
    .symbol:         _Z4mega4Args.kd
    .uniform_work_group_size: 1
    .uses_dynamic_stack: false
    .vgpr_count:     255
    .vgpr_spill_count: 0
    .wavefront_size: 64
